# queue fillers: transposes (512 half items) then combine chunks with loads 4 tokens ahead; phase-0 keeps only w_in transpose
# speedup vs baseline: 1.0029x; 1.0029x over previous
; DI unsigned cvt_pk_bf16(float lo, float hi) { unsigned r; asm("v_cvt_pk_bf16_f32 %0, %1, %2" : "=v"(r) : "v"(lo), "v"(hi)); return r; }
; DI void transpose_w(const float* __restrict__ W, int K, int N, bf16_t* __restrict__ Wt, int gtid, int gthreads) {
;   const int total = (K / 8) * N;
;   for (int id = gtid; id < total; id += gthreads) {
;     const int kc = id / N, n = id - kc * N;
;     const int rho = n & 255;
;     const int act = (n & ~255) + ((rho >> 5) & 3) * 64 + (rho >> 7) * 32 + ((rho >> 2) & 3) * 8 + ((rho >> 4) & 1) * 4 + (rho & 3);
;     const float* src = W + (size_t)(kc * 8) * N + act;
;     float v[8];
; #pragma unroll
;     for (int j = 0; j < 8; ++j) v[j] = src[(size_t)j * N];
;     uint4 o; o.x = cvt_pk_bf16(v[0], v[1]); o.y = cvt_pk_bf16(v[2], v[3]); o.z = cvt_pk_bf16(v[4], v[5]); o.w = cvt_pk_bf16(v[6], v[7]);
;     *(uint4*)(Wt + (size_t)n * K + kc * 8) = o;
;   }
; }
.Lq2_dispatch:
	s_cmpk_gt_i32 s12, 3119
	s_cbranch_scc1 .LBB0_953
	s_cmpk_gt_i32 s12, 2607
	s_cbranch_scc1 .Lcq_item
.Ltq_item:
	v_readlane_b32 s4, v236, 20
	v_readlane_b32 s5, v236, 21
	s_sub_i32 s3, s12, 2096
	s_and_b32 s13, s3, 0xff
	v_lshl_add_u32 v0, s13, 9, v202
	s_nop 3
	s_load_dwordx2 s[6:7], s[4:5], 0x50
	s_load_dwordx4 s[8:11], s[4:5], 0x60
	v_and_b32_e32 v1, 0x3ff, v0
	v_lshrrev_b32_e32 v2, 10, v0
	v_and_b32_e32 v3, 0xffffff03, v1
	v_and_b32_e32 v9, 0x60, v1
	v_lshl_or_b32 v3, v9, 1, v3
	v_and_b32_e32 v9, 0x0c, v1
	v_lshl_or_b32 v3, v9, 1, v3
	v_bfe_u32 v9, v1, 7, 1
	v_lshl_or_b32 v3, v9, 5, v3
	v_bfe_u32 v9, v1, 4, 1
	v_lshl_or_b32 v3, v9, 2, v3
	v_lshlrev_b32_e32 v3, 2, v3
	v_lshl_or_b32 v3, v2, 15, v3
	v_lshlrev_b32_e32 v2, 4, v2
	v_lshl_or_b32 v4, v1, 11, v2
	v_lshl_or_b32 v5, v1, 13, v2
	v_add_u32_e32 v4, 0x800000, v4
	v_add_u32_e32 v5, 0x1200000, v5
	v_and_b32_e32 v1, 0xfff, v0
	v_lshrrev_b32_e32 v2, 12, v0
	v_and_b32_e32 v6, 0xffffff03, v1
	v_and_b32_e32 v9, 0x60, v1
	v_lshl_or_b32 v6, v9, 1, v6
	v_and_b32_e32 v9, 0x0c, v1
	v_lshl_or_b32 v6, v9, 1, v6
	v_bfe_u32 v9, v1, 7, 1
	v_lshl_or_b32 v6, v9, 5, v6
	v_bfe_u32 v9, v1, 4, 1
	v_lshl_or_b32 v6, v9, 2, v6
	v_lshlrev_b32_e32 v6, 2, v6
	v_lshl_or_b32 v6, v2, 17, v6
	v_lshlrev_b32_e32 v2, 4, v2
	v_lshl_or_b32 v7, v1, 11, v2
	v_add_u32_e32 v7, 0xa00000, v7
	s_waitcnt lgkmcnt(0)
	s_cmpk_gt_u32 s3, 0xff
	s_cbranch_scc1 .Ltq_second
	global_load_dword v16, v3, s[6:7]
	v_add_u32_e32 v49, 0x1000, v3
	global_load_dword v17, v49, s[6:7]
	v_add_u32_e32 v50, 0x2000, v3
	global_load_dword v18, v50, s[6:7]
	v_add_u32_e32 v51, 0x3000, v3
	global_load_dword v19, v51, s[6:7]
	v_add_u32_e32 v52, 0x4000, v3
	global_load_dword v20, v52, s[6:7]
	v_add_u32_e32 v53, 0x5000, v3
	global_load_dword v21, v53, s[6:7]
	v_add_u32_e32 v54, 0x6000, v3
	global_load_dword v22, v54, s[6:7]
	v_add_u32_e32 v55, 0x7000, v3
	global_load_dword v23, v55, s[6:7]
	global_load_dword v24, v6, s[8:9]
	v_add_u32_e32 v49, 0x4000, v6
	global_load_dword v25, v49, s[8:9]
	v_add_u32_e32 v50, 0x8000, v6
	global_load_dword v26, v50, s[8:9]
	v_add_u32_e32 v51, 0xc000, v6
	global_load_dword v27, v51, s[8:9]
	v_add_u32_e32 v52, 0x10000, v6
	global_load_dword v28, v52, s[8:9]
	v_add_u32_e32 v53, 0x14000, v6
	global_load_dword v29, v53, s[8:9]
	v_add_u32_e32 v54, 0x18000, v6
	global_load_dword v30, v54, s[8:9]
	v_add_u32_e32 v55, 0x1c000, v6
	global_load_dword v31, v55, s[8:9]
	v_add_u32_e32 v48, 0x400000, v6
	global_load_dword v32, v48, s[8:9]
	v_add_u32_e32 v49, 0x404000, v6
	global_load_dword v33, v49, s[8:9]
	v_add_u32_e32 v50, 0x408000, v6
	global_load_dword v34, v50, s[8:9]
	v_add_u32_e32 v51, 0x40c000, v6
	global_load_dword v35, v51, s[8:9]
	v_add_u32_e32 v52, 0x410000, v6
	global_load_dword v36, v52, s[8:9]
	v_add_u32_e32 v53, 0x414000, v6
	global_load_dword v37, v53, s[8:9]
	v_add_u32_e32 v54, 0x418000, v6
	global_load_dword v38, v54, s[8:9]
	v_add_u32_e32 v55, 0x41c000, v6
	global_load_dword v39, v55, s[8:9]
	v_add_u32_e32 v48, 0x800000, v6
	global_load_dword v40, v48, s[8:9]
	v_add_u32_e32 v49, 0x804000, v6
	global_load_dword v41, v49, s[8:9]
	v_add_u32_e32 v50, 0x808000, v6
	global_load_dword v42, v50, s[8:9]
	v_add_u32_e32 v51, 0x80c000, v6
	global_load_dword v43, v51, s[8:9]
	v_add_u32_e32 v52, 0x810000, v6
	global_load_dword v44, v52, s[8:9]
	v_add_u32_e32 v53, 0x814000, v6
	global_load_dword v45, v53, s[8:9]
	v_add_u32_e32 v54, 0x818000, v6
	global_load_dword v46, v54, s[8:9]
	v_add_u32_e32 v55, 0x81c000, v6
	global_load_dword v47, v55, s[8:9]
	s_waitcnt vmcnt(24)
	v_cvt_pk_bf16_f32 v56, v16, v17
	v_cvt_pk_bf16_f32 v57, v18, v19
	v_cvt_pk_bf16_f32 v58, v20, v21
	v_cvt_pk_bf16_f32 v59, v22, v23
	global_store_dwordx4 v4, v[56:59], s[58:59]
	v_add_u32_e32 v48, 0xc00000, v6
	global_load_dword v16, v48, s[8:9]
	v_add_u32_e32 v49, 0xc04000, v6
	global_load_dword v17, v49, s[8:9]
	v_add_u32_e32 v50, 0xc08000, v6
	global_load_dword v18, v50, s[8:9]
	v_add_u32_e32 v51, 0xc0c000, v6
	global_load_dword v19, v51, s[8:9]
	v_add_u32_e32 v52, 0xc10000, v6
	global_load_dword v20, v52, s[8:9]
	v_add_u32_e32 v53, 0xc14000, v6
	global_load_dword v21, v53, s[8:9]
	v_add_u32_e32 v54, 0xc18000, v6
	global_load_dword v22, v54, s[8:9]
	v_add_u32_e32 v55, 0xc1c000, v6
	global_load_dword v23, v55, s[8:9]
	s_waitcnt vmcnt(25)
	v_cvt_pk_bf16_f32 v60, v24, v25
	v_cvt_pk_bf16_f32 v61, v26, v27
	v_cvt_pk_bf16_f32 v62, v28, v29
	v_cvt_pk_bf16_f32 v63, v30, v31
	global_store_dwordx4 v7, v[60:63], s[58:59]
	s_waitcnt vmcnt(18)
	v_cvt_pk_bf16_f32 v56, v32, v33
	v_cvt_pk_bf16_f32 v57, v34, v35
	v_cvt_pk_bf16_f32 v58, v36, v37
	v_cvt_pk_bf16_f32 v59, v38, v39
	v_add_u32_e32 v10, 0x200, v7
	global_store_dwordx4 v10, v[56:59], s[58:59]
	s_waitcnt vmcnt(11)
	v_cvt_pk_bf16_f32 v60, v40, v41
	v_cvt_pk_bf16_f32 v61, v42, v43
	v_cvt_pk_bf16_f32 v62, v44, v45
	v_cvt_pk_bf16_f32 v63, v46, v47
	v_add_u32_e32 v10, 0x400, v7
	global_store_dwordx4 v10, v[60:63], s[58:59]
	s_waitcnt vmcnt(3)
	v_cvt_pk_bf16_f32 v56, v16, v17
	v_cvt_pk_bf16_f32 v57, v18, v19
	v_cvt_pk_bf16_f32 v58, v20, v21
	v_cvt_pk_bf16_f32 v59, v22, v23
	v_add_u32_e32 v10, 0x600, v7
	global_store_dwordx4 v10, v[56:59], s[58:59]
	s_branch .LBB0_952
; DI unsigned cvt_pk_bf16(float lo, float hi) { unsigned r; asm("v_cvt_pk_bf16_f32 %0, %1, %2" : "=v"(r) : "v"(lo), "v"(hi)); return r; }
; DI void transpose_w(const float* __restrict__ W, int K, int N, bf16_t* __restrict__ Wt, int gtid, int gthreads) {
;   const int total = (K / 8) * N;
;   for (int id = gtid; id < total; id += gthreads) {
;     const int kc = id / N, n = id - kc * N;
;     const int rho = n & 255;
;     const int act = (n & ~255) + ((rho >> 5) & 3) * 64 + (rho >> 7) * 32 + ((rho >> 2) & 3) * 8 + ((rho >> 4) & 1) * 4 + (rho & 3);
;     const float* src = W + (size_t)(kc * 8) * N + act;
;     float v[8];
; #pragma unroll
;     for (int j = 0; j < 8; ++j) v[j] = src[(size_t)j * N];
;     uint4 o; o.x = cvt_pk_bf16(v[0], v[1]); o.y = cvt_pk_bf16(v[2], v[3]); o.z = cvt_pk_bf16(v[4], v[5]); o.w = cvt_pk_bf16(v[6], v[7]);
;     *(uint4*)(Wt + (size_t)n * K + kc * 8) = o;
;   }
; }
.Ltq_second:
	global_load_dword v16, v3, s[10:11]
	v_add_u32_e32 v49, 0x1000, v3
	global_load_dword v17, v49, s[10:11]
	v_add_u32_e32 v50, 0x2000, v3
	global_load_dword v18, v50, s[10:11]
	v_add_u32_e32 v51, 0x3000, v3
	global_load_dword v19, v51, s[10:11]
	v_add_u32_e32 v52, 0x4000, v3
	global_load_dword v20, v52, s[10:11]
	v_add_u32_e32 v53, 0x5000, v3
	global_load_dword v21, v53, s[10:11]
	v_add_u32_e32 v54, 0x6000, v3
	global_load_dword v22, v54, s[10:11]
	v_add_u32_e32 v55, 0x7000, v3
	global_load_dword v23, v55, s[10:11]
	v_add_u32_e32 v48, 0x400000, v3
	global_load_dword v24, v48, s[10:11]
	v_add_u32_e32 v49, 0x401000, v3
	global_load_dword v25, v49, s[10:11]
	v_add_u32_e32 v50, 0x402000, v3
	global_load_dword v26, v50, s[10:11]
	v_add_u32_e32 v51, 0x403000, v3
	global_load_dword v27, v51, s[10:11]
	v_add_u32_e32 v52, 0x404000, v3
	global_load_dword v28, v52, s[10:11]
	v_add_u32_e32 v53, 0x405000, v3
	global_load_dword v29, v53, s[10:11]
	v_add_u32_e32 v54, 0x406000, v3
	global_load_dword v30, v54, s[10:11]
	v_add_u32_e32 v55, 0x407000, v3
	global_load_dword v31, v55, s[10:11]
	v_add_u32_e32 v48, 0x800000, v3
	global_load_dword v32, v48, s[10:11]
	v_add_u32_e32 v49, 0x801000, v3
	global_load_dword v33, v49, s[10:11]
	v_add_u32_e32 v50, 0x802000, v3
	global_load_dword v34, v50, s[10:11]
	v_add_u32_e32 v51, 0x803000, v3
	global_load_dword v35, v51, s[10:11]
	v_add_u32_e32 v52, 0x804000, v3
	global_load_dword v36, v52, s[10:11]
	v_add_u32_e32 v53, 0x805000, v3
	global_load_dword v37, v53, s[10:11]
	v_add_u32_e32 v54, 0x806000, v3
	global_load_dword v38, v54, s[10:11]
	v_add_u32_e32 v55, 0x807000, v3
	global_load_dword v39, v55, s[10:11]
	v_add_u32_e32 v48, 0xc00000, v3
	global_load_dword v40, v48, s[10:11]
	v_add_u32_e32 v49, 0xc01000, v3
	global_load_dword v41, v49, s[10:11]
	v_add_u32_e32 v50, 0xc02000, v3
	global_load_dword v42, v50, s[10:11]
	v_add_u32_e32 v51, 0xc03000, v3
	global_load_dword v43, v51, s[10:11]
	v_add_u32_e32 v52, 0xc04000, v3
	global_load_dword v44, v52, s[10:11]
	v_add_u32_e32 v53, 0xc05000, v3
	global_load_dword v45, v53, s[10:11]
	v_add_u32_e32 v54, 0xc06000, v3
	global_load_dword v46, v54, s[10:11]
	v_add_u32_e32 v55, 0xc07000, v3
	global_load_dword v47, v55, s[10:11]
	s_waitcnt vmcnt(24)
	v_cvt_pk_bf16_f32 v56, v16, v17
	v_cvt_pk_bf16_f32 v57, v18, v19
	v_cvt_pk_bf16_f32 v58, v20, v21
	v_cvt_pk_bf16_f32 v59, v22, v23
	global_store_dwordx4 v5, v[56:59], s[58:59]
	s_waitcnt vmcnt(17)
	v_cvt_pk_bf16_f32 v60, v24, v25
	v_cvt_pk_bf16_f32 v61, v26, v27
	v_cvt_pk_bf16_f32 v62, v28, v29
	v_cvt_pk_bf16_f32 v63, v30, v31
	v_add_u32_e32 v10, 0x800, v5
	global_store_dwordx4 v10, v[60:63], s[58:59]
	s_waitcnt vmcnt(10)
	v_cvt_pk_bf16_f32 v56, v32, v33
	v_cvt_pk_bf16_f32 v57, v34, v35
	v_cvt_pk_bf16_f32 v58, v36, v37
	v_cvt_pk_bf16_f32 v59, v38, v39
	v_add_u32_e32 v10, 0x1000, v5
	global_store_dwordx4 v10, v[56:59], s[58:59]
	s_waitcnt vmcnt(3)
	v_cvt_pk_bf16_f32 v60, v40, v41
	v_cvt_pk_bf16_f32 v61, v42, v43
	v_cvt_pk_bf16_f32 v62, v44, v45
	v_cvt_pk_bf16_f32 v63, v46, v47
	v_add_u32_e32 v10, 0x1800, v5
	global_store_dwordx4 v10, v[60:63], s[58:59]
	s_branch .LBB0_952
.Lcq_item:
	s_and_saveexec_b64 s[0:1], s[84:85]
	s_cbranch_execz .Lcq_go
	v_mov_b32_e32 v0, 0

; DI void phase_combine(const Params& p) {
;   const int lane = threadIdx.x & 63, wave = threadIdx.x >> 6;
;   const unsigned* ofw = (const unsigned*)p.out; const unsigned* obw = (const unsigned*)((const bf16_t*)p.out + (size_t)NTOK * 512);
;   const unsigned* GH = (const unsigned*)(p.ws + WS_GH);
;   bf16_t* OC = (bf16_t*)(p.ws + WS_OCAT);
;   const float w0 = p.hgrn_norm_w[lane * 2], w1 = p.hgrn_norm_w[lane * 2 + 1];
;   for (int tok = blockIdx.x * 8 + wave; tok < NTOK; tok += gridDim.x * 8) {
;     unsigned a[4], b[4], g[4];
; #pragma unroll
;     for (int hh = 0; hh < 4; ++hh) { const size_t idx = ((size_t)tok * 512 + hh * 128 + lane * 2) >> 1; a[hh] = ofw[idx]; b[hh] = obw[idx]; g[hh] = GH[idx]; }
.Lcq_go:
	s_or_b64 exec, exec, s[0:1]
	s_barrier
	s_sub_i32 s3, s12, 2608
	s_lshl_b32 s3, s3, 7
	v_lshrrev_b32_e32 v0, 6, v202
	v_add_u32_e32 v0, s3, v0
	v_and_b32_e32 v4, 0x7e, v203
	v_lshlrev_b32_e32 v1, 2, v4
	global_load_dwordx2 v[2:3], v1, s[46:47]
	s_add_u32 s6, s56, 0x4000000
	s_addc_u32 s7, s57, 0
	s_add_u32 s8, s58, 0x26000000
	s_addc_u32 s9, s59, 0
	v_cmp_lt_i32_e32 vcc, v206, v205
	s_nop 1
	v_cndmask_b32_e32 v1, v204, v206, vcc
	v_lshlrev_b32_e32 v8, 2, v1
	v_cmp_lt_i32_e32 vcc, v207, v205
	s_nop 1
	v_cndmask_b32_e32 v1, v204, v207, vcc
	v_lshlrev_b32_e32 v9, 2, v1
	v_cmp_lt_i32_e32 vcc, v211, v205
	s_nop 1
	v_cndmask_b32_e32 v1, v204, v211, vcc
	v_lshlrev_b32_e32 v10, 2, v1
	v_cmp_lt_i32_e32 vcc, v210, v205
	s_nop 1
	v_cndmask_b32_e32 v1, v204, v210, vcc
	v_lshlrev_b32_e32 v11, 2, v1
	v_cmp_lt_i32_e32 vcc, v209, v205
	s_nop 1
	v_cndmask_b32_e32 v1, v204, v209, vcc
	v_lshlrev_b32_e32 v12, 2, v1
	v_cmp_lt_i32_e32 vcc, v208, v205
	s_nop 1
	v_cndmask_b32_e32 v1, v204, v208, vcc
	v_lshlrev_b32_e32 v13, 2, v1
	v_mov_b32_e32 v5, 0
	v_lshlrev_b32_e32 v4, 1, v4
	s_mov_b64 s[12:13], 0x2a000400
	s_mov_b64 s[10:11], 0x2000
	s_mov_b64 s[16:17], 0x4000
	v_mov_b32_e32 v14, 0x358637bd
	s_mov_b32 s14, 0x800000
	v_ashrrev_i32_e32 v1, 31, v0
	v_lshlrev_b64 v[90:91], 10, v[0:1]
	v_or_b32_e32 v90, v90, v4
	v_lshl_add_u64 v[92:93], s[56:57], 0, v[90:91]
	v_lshl_add_u64 v[94:95], s[6:7], 0, v[90:91]
	v_lshl_add_u64 v[96:97], s[8:9], 0, v[90:91]
	v_lshlrev_b64 v[98:99], 11, v[0:1]
	v_lshl_add_u64 v[98:99], s[58:59], 0, v[98:99]
	v_lshl_add_u64 v[98:99], v[98:99], 0, v[4:5]
	v_lshl_add_u64 v[98:99], v[98:99], 0, s[12:13]
	global_load_dword v104, v[92:93], off
	global_load_dword v105, v[92:93], off offset:256
	global_load_dword v106, v[92:93], off offset:512
	global_load_dword v107, v[92:93], off offset:768
	global_load_dword v108, v[94:95], off
	global_load_dword v109, v[94:95], off offset:256
	global_load_dword v110, v[94:95], off offset:512
	global_load_dword v111, v[94:95], off offset:768
	global_load_dword v112, v[96:97], off
	global_load_dword v113, v[96:97], off offset:256
	global_load_dword v114, v[96:97], off offset:512
	global_load_dword v115, v[96:97], off offset:768
	v_lshl_add_u64 v[92:93], v[92:93], 0, s[10:11]
	v_lshl_add_u64 v[94:95], v[94:95], 0, s[10:11]
	v_lshl_add_u64 v[96:97], v[96:97], 0, s[10:11]
	global_load_dword v116, v[92:93], off
	global_load_dword v117, v[92:93], off offset:256
	global_load_dword v118, v[92:93], off offset:512
	global_load_dword v119, v[92:93], off offset:768
	global_load_dword v120, v[94:95], off
	global_load_dword v121, v[94:95], off offset:256
	global_load_dword v122, v[94:95], off offset:512
	global_load_dword v123, v[94:95], off offset:768
	global_load_dword v124, v[96:97], off
	global_load_dword v125, v[96:97], off offset:256
	global_load_dword v126, v[96:97], off offset:512
	global_load_dword v127, v[96:97], off offset:768
	v_lshl_add_u64 v[92:93], v[92:93], 0, s[10:11]
	v_lshl_add_u64 v[94:95], v[94:95], 0, s[10:11]
	v_lshl_add_u64 v[96:97], v[96:97], 0, s[10:11]
	global_load_dword v128, v[92:93], off
	global_load_dword v129, v[92:93], off offset:256
	global_load_dword v130, v[92:93], off offset:512
	global_load_dword v131, v[92:93], off offset:768
	global_load_dword v132, v[94:95], off
	global_load_dword v133, v[94:95], off offset:256
	global_load_dword v134, v[94:95], off offset:512
	global_load_dword v135, v[94:95], off offset:768
	global_load_dword v136, v[96:97], off
	global_load_dword v137, v[96:97], off offset:256
	global_load_dword v138, v[96:97], off offset:512
	global_load_dword v139, v[96:97], off offset:768
	v_lshl_add_u64 v[92:93], v[92:93], 0, s[10:11]
	v_lshl_add_u64 v[94:95], v[94:95], 0, s[10:11]
	v_lshl_add_u64 v[96:97], v[96:97], 0, s[10:11]
	global_load_dword v140, v[92:93], off
	global_load_dword v141, v[92:93], off offset:256
	global_load_dword v142, v[92:93], off offset:512
	global_load_dword v143, v[92:93], off offset:768
	global_load_dword v144, v[94:95], off
	global_load_dword v145, v[94:95], off offset:256
	global_load_dword v146, v[94:95], off offset:512
	global_load_dword v147, v[94:95], off offset:768
	global_load_dword v148, v[96:97], off
	global_load_dword v149, v[96:97], off offset:256
	global_load_dword v150, v[96:97], off offset:512
	global_load_dword v151, v[96:97], off offset:768
	v_lshl_add_u64 v[92:93], v[92:93], 0, s[10:11]
	v_lshl_add_u64 v[94:95], v[94:95], 0, s[10:11]
	v_lshl_add_u64 v[96:97], v[96:97], 0, s[10:11]
	s_mov_b32 s98, 3
; DI unsigned cvt_pk_bf16(float lo, float hi) { unsigned r; asm("v_cvt_pk_bf16_f32 %0, %1, %2" : "=v"(r) : "v"(lo), "v"(hi)); return r; }
; DI void phase_combine(const Params& p) {
;     ...
;     for (int hh = 0; hh < 4; ++hh) { const size_t idx = ((size_t)tok * 512 + hh * 128 + lane * 2) >> 1; a[hh] = ofw[idx]; b[hh] = obw[idx]; g[hh] = GH[idx]; }
; #pragma unroll
;     for (int hh = 0; hh < 4; ++hh) {
;       const float o0 = __uint_as_float(a[hh] << 16) + __uint_as_float(b[hh] << 16), o1 = __uint_as_float(a[hh] & 0xffff0000u) + __uint_as_float(b[hh] & 0xffff0000u);
;       const float ss = wave_sum(o0 * o0 + o1 * o1);
;       const float rstd = rsqrtf(ss * (1.f / 128.f) + EPSN);
;       const float g0 = __uint_as_float(g[hh] << 16), g1 = __uint_as_float(g[hh] & 0xffff0000u);
;       *(unsigned*)(OC + (size_t)tok * 1024 + 512 + hh * 128 + lane * 2) = cvt_pk_bf16(o0 * rstd * w0 * g0, o1 * rstd * w1 * g1);
;     }
.Lcq_loop:
	s_waitcnt vmcnt(36)
	v_lshlrev_b32_e32 v64, 16, v104
	v_lshlrev_b32_e32 v76, 16, v108
	v_and_b32_e32 v68, 0xffff0000, v104
	v_and_b32_e32 v80, 0xffff0000, v108
	v_add_f32_e32 v64, v64, v76
	v_add_f32_e32 v68, v68, v80
	v_mul_f32_e32 v72, v64, v64
	v_mul_f32_e32 v76, v68, v68
	v_add_f32_e32 v72, v72, v76
	v_lshlrev_b32_e32 v65, 16, v105
	v_lshlrev_b32_e32 v77, 16, v109
	v_and_b32_e32 v69, 0xffff0000, v105
	v_and_b32_e32 v81, 0xffff0000, v109
	v_add_f32_e32 v65, v65, v77
	v_add_f32_e32 v69, v69, v81
	v_mul_f32_e32 v73, v65, v65
	v_mul_f32_e32 v77, v69, v69
	v_add_f32_e32 v73, v73, v77
	v_lshlrev_b32_e32 v66, 16, v106
	v_lshlrev_b32_e32 v78, 16, v110
	v_and_b32_e32 v70, 0xffff0000, v106
	v_and_b32_e32 v82, 0xffff0000, v110
	v_add_f32_e32 v66, v66, v78
	v_add_f32_e32 v70, v70, v82
	v_mul_f32_e32 v74, v66, v66
	v_mul_f32_e32 v78, v70, v70
	v_add_f32_e32 v74, v74, v78
	v_lshlrev_b32_e32 v67, 16, v107
	v_lshlrev_b32_e32 v79, 16, v111
	v_and_b32_e32 v71, 0xffff0000, v107
	v_and_b32_e32 v83, 0xffff0000, v111
	v_add_f32_e32 v67, v67, v79
	v_add_f32_e32 v71, v71, v83
	v_mul_f32_e32 v75, v67, v67
	v_mul_f32_e32 v79, v71, v71
	v_add_f32_e32 v75, v75, v79
	ds_bpermute_b32 v76, v8, v72
	ds_bpermute_b32 v77, v8, v73
	ds_bpermute_b32 v78, v8, v74
	ds_bpermute_b32 v79, v8, v75
	s_waitcnt lgkmcnt(3)
	v_add_f32_e32 v72, v72, v76
	s_waitcnt lgkmcnt(2)
	v_add_f32_e32 v73, v73, v77
	s_waitcnt lgkmcnt(1)
	v_add_f32_e32 v74, v74, v78
	s_waitcnt lgkmcnt(0)
	v_add_f32_e32 v75, v75, v79
	ds_bpermute_b32 v76, v9, v72
	ds_bpermute_b32 v77, v9, v73
	ds_bpermute_b32 v78, v9, v74
	ds_bpermute_b32 v79, v9, v75
	s_waitcnt lgkmcnt(3)
	v_add_f32_e32 v72, v72, v76
	s_waitcnt lgkmcnt(2)
	v_add_f32_e32 v73, v73, v77
	s_waitcnt lgkmcnt(1)
	v_add_f32_e32 v74, v74, v78
	s_waitcnt lgkmcnt(0)
	v_add_f32_e32 v75, v75, v79
	ds_bpermute_b32 v76, v10, v72
	ds_bpermute_b32 v77, v10, v73
	ds_bpermute_b32 v78, v10, v74
	ds_bpermute_b32 v79, v10, v75
	s_waitcnt lgkmcnt(3)
	v_add_f32_e32 v72, v72, v76
	s_waitcnt lgkmcnt(2)
	v_add_f32_e32 v73, v73, v77
	s_waitcnt lgkmcnt(1)
	v_add_f32_e32 v74, v74, v78
	s_waitcnt lgkmcnt(0)
	v_add_f32_e32 v75, v75, v79
	ds_bpermute_b32 v76, v11, v72
	ds_bpermute_b32 v77, v11, v73
	ds_bpermute_b32 v78, v11, v74
	ds_bpermute_b32 v79, v11, v75
	s_waitcnt lgkmcnt(3)
	v_add_f32_e32 v72, v72, v76
	s_waitcnt lgkmcnt(2)
	v_add_f32_e32 v73, v73, v77
	s_waitcnt lgkmcnt(1)
	v_add_f32_e32 v74, v74, v78
	s_waitcnt lgkmcnt(0)
	v_add_f32_e32 v75, v75, v79
	ds_bpermute_b32 v76, v12, v72
	ds_bpermute_b32 v77, v12, v73
	ds_bpermute_b32 v78, v12, v74
	ds_bpermute_b32 v79, v12, v75
	s_waitcnt lgkmcnt(3)
	v_add_f32_e32 v72, v72, v76
	s_waitcnt lgkmcnt(2)
	v_add_f32_e32 v73, v73, v77
	s_waitcnt lgkmcnt(1)
	v_add_f32_e32 v74, v74, v78
	s_waitcnt lgkmcnt(0)
	v_add_f32_e32 v75, v75, v79
	ds_bpermute_b32 v76, v13, v72
	ds_bpermute_b32 v77, v13, v73
	ds_bpermute_b32 v78, v13, v74
	ds_bpermute_b32 v79, v13, v75
	s_waitcnt lgkmcnt(3)
	v_add_f32_e32 v72, v72, v76
	s_waitcnt lgkmcnt(2)
	v_add_f32_e32 v73, v73, v77
	s_waitcnt lgkmcnt(1)
	v_add_f32_e32 v74, v74, v78
	s_waitcnt lgkmcnt(0)
	v_add_f32_e32 v75, v75, v79
	v_fmamk_f32 v80, v72, 0x3c000000, v14
	v_mul_f32_e32 v76, 0x4b800000, v80
	v_cmp_gt_f32_e32 vcc, s14, v80
	s_nop 1
	v_cndmask_b32_e32 v80, v80, v76, vcc
	v_rsq_f32_e32 v80, v80
	s_nop 0
	v_mul_f32_e32 v76, 0x45800000, v80
	v_cndmask_b32_e32 v80, v80, v76, vcc
	v_mul_f32_e32 v64, v64, v80
	v_mul_f32_e32 v68, v68, v80
	v_mul_f32_e32 v64, v2, v64
	v_mul_f32_e32 v68, v3, v68
	v_lshlrev_b32_e32 v76, 16, v112
	v_and_b32_e32 v72, 0xffff0000, v112
	v_mul_f32_e32 v64, v64, v76
	v_mul_f32_e32 v68, v68, v72
	v_cvt_pk_bf16_f32 v64, v64, v68
	global_store_dword v[98:99], v64, off
	v_fmamk_f32 v81, v73, 0x3c000000, v14
	v_mul_f32_e32 v77, 0x4b800000, v81
	v_cmp_gt_f32_e32 vcc, s14, v81
	s_nop 1
	v_cndmask_b32_e32 v81, v81, v77, vcc
	v_rsq_f32_e32 v81, v81
	s_nop 0
	v_mul_f32_e32 v77, 0x45800000, v81
	v_cndmask_b32_e32 v81, v81, v77, vcc
	v_mul_f32_e32 v65, v65, v81
	v_mul_f32_e32 v69, v69, v81
	v_mul_f32_e32 v65, v2, v65
	v_mul_f32_e32 v69, v3, v69
	v_lshlrev_b32_e32 v77, 16, v113
	v_and_b32_e32 v73, 0xffff0000, v113
	v_mul_f32_e32 v65, v65, v77
	v_mul_f32_e32 v69, v69, v73
	v_cvt_pk_bf16_f32 v65, v65, v69
	global_store_dword v[98:99], v65, off offset:256
	v_fmamk_f32 v82, v74, 0x3c000000, v14
	v_mul_f32_e32 v78, 0x4b800000, v82
	v_cmp_gt_f32_e32 vcc, s14, v82
	s_nop 1
	v_cndmask_b32_e32 v82, v82, v78, vcc
	v_rsq_f32_e32 v82, v82
	s_nop 0
	v_mul_f32_e32 v78, 0x45800000, v82
	v_cndmask_b32_e32 v82, v82, v78, vcc
	v_mul_f32_e32 v66, v66, v82
	v_mul_f32_e32 v70, v70, v82
	v_mul_f32_e32 v66, v2, v66
	v_mul_f32_e32 v70, v3, v70
	v_lshlrev_b32_e32 v78, 16, v114
	v_and_b32_e32 v74, 0xffff0000, v114
	v_mul_f32_e32 v66, v66, v78
	v_mul_f32_e32 v70, v70, v74
	v_cvt_pk_bf16_f32 v66, v66, v70
	global_store_dword v[98:99], v66, off offset:512
	v_fmamk_f32 v83, v75, 0x3c000000, v14
	v_mul_f32_e32 v79, 0x4b800000, v83
	v_cmp_gt_f32_e32 vcc, s14, v83
	s_nop 1
	v_cndmask_b32_e32 v83, v83, v79, vcc
	v_rsq_f32_e32 v83, v83
	s_nop 0
	v_mul_f32_e32 v79, 0x45800000, v83
	v_cndmask_b32_e32 v83, v83, v79, vcc
	v_mul_f32_e32 v67, v67, v83
	v_mul_f32_e32 v71, v71, v83
	v_mul_f32_e32 v67, v2, v67
	v_mul_f32_e32 v71, v3, v71
	v_lshlrev_b32_e32 v79, 16, v115
	v_and_b32_e32 v75, 0xffff0000, v115
	v_mul_f32_e32 v67, v67, v79
	v_mul_f32_e32 v71, v71, v75
	v_cvt_pk_bf16_f32 v67, v67, v71
	global_store_dword v[98:99], v67, off offset:768
	v_lshl_add_u64 v[98:99], v[98:99], 0, s[16:17]
	global_load_dword v104, v[92:93], off
	global_load_dword v105, v[92:93], off offset:256
	global_load_dword v106, v[92:93], off offset:512
	global_load_dword v107, v[92:93], off offset:768
	global_load_dword v108, v[94:95], off
	global_load_dword v109, v[94:95], off offset:256
	global_load_dword v110, v[94:95], off offset:512
	global_load_dword v111, v[94:95], off offset:768
	global_load_dword v112, v[96:97], off
	global_load_dword v113, v[96:97], off offset:256
	global_load_dword v114, v[96:97], off offset:512
	global_load_dword v115, v[96:97], off offset:768
	v_lshl_add_u64 v[92:93], v[92:93], 0, s[10:11]
	v_lshl_add_u64 v[94:95], v[94:95], 0, s[10:11]
	v_lshl_add_u64 v[96:97], v[96:97], 0, s[10:11]
	s_waitcnt vmcnt(40)
; DI unsigned cvt_pk_bf16(float lo, float hi) { unsigned r; asm("v_cvt_pk_bf16_f32 %0, %1, %2" : "=v"(r) : "v"(lo), "v"(hi)); return r; }
; DI void phase_combine(const Params& p) {
;     ...
;     for (int hh = 0; hh < 4; ++hh) { const size_t idx = ((size_t)tok * 512 + hh * 128 + lane * 2) >> 1; a[hh] = ofw[idx]; b[hh] = obw[idx]; g[hh] = GH[idx]; }
; #pragma unroll
;     for (int hh = 0; hh < 4; ++hh) {
;       const float o0 = __uint_as_float(a[hh] << 16) + __uint_as_float(b[hh] << 16), o1 = __uint_as_float(a[hh] & 0xffff0000u) + __uint_as_float(b[hh] & 0xffff0000u);
;       const float ss = wave_sum(o0 * o0 + o1 * o1);
;       const float rstd = rsqrtf(ss * (1.f / 128.f) + EPSN);
;       const float g0 = __uint_as_float(g[hh] << 16), g1 = __uint_as_float(g[hh] & 0xffff0000u);
;       *(unsigned*)(OC + (size_t)tok * 1024 + 512 + hh * 128 + lane * 2) = cvt_pk_bf16(o0 * rstd * w0 * g0, o1 * rstd * w1 * g1);
;     }
	v_lshlrev_b32_e32 v64, 16, v116
	v_lshlrev_b32_e32 v76, 16, v120
	v_and_b32_e32 v68, 0xffff0000, v116
	v_and_b32_e32 v80, 0xffff0000, v120
	v_add_f32_e32 v64, v64, v76
	v_add_f32_e32 v68, v68, v80
	v_mul_f32_e32 v72, v64, v64
	v_mul_f32_e32 v76, v68, v68
	v_add_f32_e32 v72, v72, v76
	v_lshlrev_b32_e32 v65, 16, v117
	v_lshlrev_b32_e32 v77, 16, v121
	v_and_b32_e32 v69, 0xffff0000, v117
	v_and_b32_e32 v81, 0xffff0000, v121
	v_add_f32_e32 v65, v65, v77
	v_add_f32_e32 v69, v69, v81
	v_mul_f32_e32 v73, v65, v65
	v_mul_f32_e32 v77, v69, v69
	v_add_f32_e32 v73, v73, v77
	v_lshlrev_b32_e32 v66, 16, v118
	v_lshlrev_b32_e32 v78, 16, v122
	v_and_b32_e32 v70, 0xffff0000, v118
	v_and_b32_e32 v82, 0xffff0000, v122
	v_add_f32_e32 v66, v66, v78
	v_add_f32_e32 v70, v70, v82
	v_mul_f32_e32 v74, v66, v66
	v_mul_f32_e32 v78, v70, v70
	v_add_f32_e32 v74, v74, v78
	v_lshlrev_b32_e32 v67, 16, v119
	v_lshlrev_b32_e32 v79, 16, v123
	v_and_b32_e32 v71, 0xffff0000, v119
	v_and_b32_e32 v83, 0xffff0000, v123
	v_add_f32_e32 v67, v67, v79
	v_add_f32_e32 v71, v71, v83
	v_mul_f32_e32 v75, v67, v67
	v_mul_f32_e32 v79, v71, v71
	v_add_f32_e32 v75, v75, v79
	ds_bpermute_b32 v76, v8, v72
	ds_bpermute_b32 v77, v8, v73
	ds_bpermute_b32 v78, v8, v74
	ds_bpermute_b32 v79, v8, v75
	s_waitcnt lgkmcnt(3)
	v_add_f32_e32 v72, v72, v76
	s_waitcnt lgkmcnt(2)
	v_add_f32_e32 v73, v73, v77
	s_waitcnt lgkmcnt(1)
	v_add_f32_e32 v74, v74, v78
	s_waitcnt lgkmcnt(0)
	v_add_f32_e32 v75, v75, v79
	ds_bpermute_b32 v76, v9, v72
	ds_bpermute_b32 v77, v9, v73
	ds_bpermute_b32 v78, v9, v74
	ds_bpermute_b32 v79, v9, v75
	s_waitcnt lgkmcnt(3)
	v_add_f32_e32 v72, v72, v76
	s_waitcnt lgkmcnt(2)
	v_add_f32_e32 v73, v73, v77
	s_waitcnt lgkmcnt(1)
	v_add_f32_e32 v74, v74, v78
	s_waitcnt lgkmcnt(0)
	v_add_f32_e32 v75, v75, v79
	ds_bpermute_b32 v76, v10, v72
	ds_bpermute_b32 v77, v10, v73
	ds_bpermute_b32 v78, v10, v74
	ds_bpermute_b32 v79, v10, v75
	s_waitcnt lgkmcnt(3)
	v_add_f32_e32 v72, v72, v76
	s_waitcnt lgkmcnt(2)
	v_add_f32_e32 v73, v73, v77
	s_waitcnt lgkmcnt(1)
	v_add_f32_e32 v74, v74, v78
	s_waitcnt lgkmcnt(0)
	v_add_f32_e32 v75, v75, v79
	ds_bpermute_b32 v76, v11, v72
	ds_bpermute_b32 v77, v11, v73
	ds_bpermute_b32 v78, v11, v74
	ds_bpermute_b32 v79, v11, v75
	s_waitcnt lgkmcnt(3)
	v_add_f32_e32 v72, v72, v76
	s_waitcnt lgkmcnt(2)
	v_add_f32_e32 v73, v73, v77
	s_waitcnt lgkmcnt(1)
	v_add_f32_e32 v74, v74, v78
	s_waitcnt lgkmcnt(0)
	v_add_f32_e32 v75, v75, v79
	ds_bpermute_b32 v76, v12, v72
	ds_bpermute_b32 v77, v12, v73
	ds_bpermute_b32 v78, v12, v74
	ds_bpermute_b32 v79, v12, v75
	s_waitcnt lgkmcnt(3)
	v_add_f32_e32 v72, v72, v76
	s_waitcnt lgkmcnt(2)
	v_add_f32_e32 v73, v73, v77
	s_waitcnt lgkmcnt(1)
	v_add_f32_e32 v74, v74, v78
	s_waitcnt lgkmcnt(0)
	v_add_f32_e32 v75, v75, v79
	ds_bpermute_b32 v76, v13, v72
	ds_bpermute_b32 v77, v13, v73
	ds_bpermute_b32 v78, v13, v74
	ds_bpermute_b32 v79, v13, v75
	s_waitcnt lgkmcnt(3)
	v_add_f32_e32 v72, v72, v76
	s_waitcnt lgkmcnt(2)
	v_add_f32_e32 v73, v73, v77
	s_waitcnt lgkmcnt(1)
	v_add_f32_e32 v74, v74, v78
	s_waitcnt lgkmcnt(0)
	v_add_f32_e32 v75, v75, v79
	v_fmamk_f32 v80, v72, 0x3c000000, v14
	v_mul_f32_e32 v76, 0x4b800000, v80
	v_cmp_gt_f32_e32 vcc, s14, v80
	s_nop 1
	v_cndmask_b32_e32 v80, v80, v76, vcc
	v_rsq_f32_e32 v80, v80
	s_nop 0
	v_mul_f32_e32 v76, 0x45800000, v80
	v_cndmask_b32_e32 v80, v80, v76, vcc
	v_mul_f32_e32 v64, v64, v80
	v_mul_f32_e32 v68, v68, v80
	v_mul_f32_e32 v64, v2, v64
	v_mul_f32_e32 v68, v3, v68
	v_lshlrev_b32_e32 v76, 16, v124
	v_and_b32_e32 v72, 0xffff0000, v124
	v_mul_f32_e32 v64, v64, v76
	v_mul_f32_e32 v68, v68, v72
	v_cvt_pk_bf16_f32 v64, v64, v68
	global_store_dword v[98:99], v64, off
	v_fmamk_f32 v81, v73, 0x3c000000, v14
	v_mul_f32_e32 v77, 0x4b800000, v81
	v_cmp_gt_f32_e32 vcc, s14, v81
	s_nop 1
	v_cndmask_b32_e32 v81, v81, v77, vcc
	v_rsq_f32_e32 v81, v81
	s_nop 0
	v_mul_f32_e32 v77, 0x45800000, v81
	v_cndmask_b32_e32 v81, v81, v77, vcc
	v_mul_f32_e32 v65, v65, v81
	v_mul_f32_e32 v69, v69, v81
	v_mul_f32_e32 v65, v2, v65
	v_mul_f32_e32 v69, v3, v69
	v_lshlrev_b32_e32 v77, 16, v125
	v_and_b32_e32 v73, 0xffff0000, v125
	v_mul_f32_e32 v65, v65, v77
	v_mul_f32_e32 v69, v69, v73
	v_cvt_pk_bf16_f32 v65, v65, v69
	global_store_dword v[98:99], v65, off offset:256
	v_fmamk_f32 v82, v74, 0x3c000000, v14
	v_mul_f32_e32 v78, 0x4b800000, v82
	v_cmp_gt_f32_e32 vcc, s14, v82
	s_nop 1
	v_cndmask_b32_e32 v82, v82, v78, vcc
	v_rsq_f32_e32 v82, v82
	s_nop 0
	v_mul_f32_e32 v78, 0x45800000, v82
	v_cndmask_b32_e32 v82, v82, v78, vcc
	v_mul_f32_e32 v66, v66, v82
	v_mul_f32_e32 v70, v70, v82
	v_mul_f32_e32 v66, v2, v66
	v_mul_f32_e32 v70, v3, v70
	v_lshlrev_b32_e32 v78, 16, v126
	v_and_b32_e32 v74, 0xffff0000, v126
	v_mul_f32_e32 v66, v66, v78
	v_mul_f32_e32 v70, v70, v74
	v_cvt_pk_bf16_f32 v66, v66, v70
	global_store_dword v[98:99], v66, off offset:512
	v_fmamk_f32 v83, v75, 0x3c000000, v14
	v_mul_f32_e32 v79, 0x4b800000, v83
	v_cmp_gt_f32_e32 vcc, s14, v83
	s_nop 1
	v_cndmask_b32_e32 v83, v83, v79, vcc
	v_rsq_f32_e32 v83, v83
	s_nop 0
	v_mul_f32_e32 v79, 0x45800000, v83
	v_cndmask_b32_e32 v83, v83, v79, vcc
	v_mul_f32_e32 v67, v67, v83
	v_mul_f32_e32 v71, v71, v83
	v_mul_f32_e32 v67, v2, v67
	v_mul_f32_e32 v71, v3, v71
	v_lshlrev_b32_e32 v79, 16, v127
	v_and_b32_e32 v75, 0xffff0000, v127
	v_mul_f32_e32 v67, v67, v79
	v_mul_f32_e32 v71, v71, v75
	v_cvt_pk_bf16_f32 v67, v67, v71
	global_store_dword v[98:99], v67, off offset:768
	v_lshl_add_u64 v[98:99], v[98:99], 0, s[16:17]
	global_load_dword v116, v[92:93], off
	global_load_dword v117, v[92:93], off offset:256
	global_load_dword v118, v[92:93], off offset:512
	global_load_dword v119, v[92:93], off offset:768
	global_load_dword v120, v[94:95], off
	global_load_dword v121, v[94:95], off offset:256
	global_load_dword v122, v[94:95], off offset:512
	global_load_dword v123, v[94:95], off offset:768
	global_load_dword v124, v[96:97], off
	global_load_dword v125, v[96:97], off offset:256
	global_load_dword v126, v[96:97], off offset:512
	global_load_dword v127, v[96:97], off offset:768
	v_lshl_add_u64 v[92:93], v[92:93], 0, s[10:11]
	v_lshl_add_u64 v[94:95], v[94:95], 0, s[10:11]
	v_lshl_add_u64 v[96:97], v[96:97], 0, s[10:11]
	s_waitcnt vmcnt(44)
; DI unsigned cvt_pk_bf16(float lo, float hi) { unsigned r; asm("v_cvt_pk_bf16_f32 %0, %1, %2" : "=v"(r) : "v"(lo), "v"(hi)); return r; }
; DI void phase_combine(const Params& p) {
;     ...
;     for (int hh = 0; hh < 4; ++hh) { const size_t idx = ((size_t)tok * 512 + hh * 128 + lane * 2) >> 1; a[hh] = ofw[idx]; b[hh] = obw[idx]; g[hh] = GH[idx]; }
; #pragma unroll
;     for (int hh = 0; hh < 4; ++hh) {
;       const float o0 = __uint_as_float(a[hh] << 16) + __uint_as_float(b[hh] << 16), o1 = __uint_as_float(a[hh] & 0xffff0000u) + __uint_as_float(b[hh] & 0xffff0000u);
;       const float ss = wave_sum(o0 * o0 + o1 * o1);
;       const float rstd = rsqrtf(ss * (1.f / 128.f) + EPSN);
;       const float g0 = __uint_as_float(g[hh] << 16), g1 = __uint_as_float(g[hh] & 0xffff0000u);
;       *(unsigned*)(OC + (size_t)tok * 1024 + 512 + hh * 128 + lane * 2) = cvt_pk_bf16(o0 * rstd * w0 * g0, o1 * rstd * w1 * g1);
;     }
	v_lshlrev_b32_e32 v64, 16, v128
	v_lshlrev_b32_e32 v76, 16, v132
	v_and_b32_e32 v68, 0xffff0000, v128
	v_and_b32_e32 v80, 0xffff0000, v132
	v_add_f32_e32 v64, v64, v76
	v_add_f32_e32 v68, v68, v80
	v_mul_f32_e32 v72, v64, v64
	v_mul_f32_e32 v76, v68, v68
	v_add_f32_e32 v72, v72, v76
	v_lshlrev_b32_e32 v65, 16, v129
	v_lshlrev_b32_e32 v77, 16, v133
	v_and_b32_e32 v69, 0xffff0000, v129
	v_and_b32_e32 v81, 0xffff0000, v133
	v_add_f32_e32 v65, v65, v77
	v_add_f32_e32 v69, v69, v81
	v_mul_f32_e32 v73, v65, v65
	v_mul_f32_e32 v77, v69, v69
	v_add_f32_e32 v73, v73, v77
	v_lshlrev_b32_e32 v66, 16, v130
	v_lshlrev_b32_e32 v78, 16, v134
	v_and_b32_e32 v70, 0xffff0000, v130
	v_and_b32_e32 v82, 0xffff0000, v134
	v_add_f32_e32 v66, v66, v78
	v_add_f32_e32 v70, v70, v82
	v_mul_f32_e32 v74, v66, v66
	v_mul_f32_e32 v78, v70, v70
	v_add_f32_e32 v74, v74, v78
	v_lshlrev_b32_e32 v67, 16, v131
	v_lshlrev_b32_e32 v79, 16, v135
	v_and_b32_e32 v71, 0xffff0000, v131
	v_and_b32_e32 v83, 0xffff0000, v135
	v_add_f32_e32 v67, v67, v79
	v_add_f32_e32 v71, v71, v83
	v_mul_f32_e32 v75, v67, v67
	v_mul_f32_e32 v79, v71, v71
	v_add_f32_e32 v75, v75, v79
	ds_bpermute_b32 v76, v8, v72
	ds_bpermute_b32 v77, v8, v73
	ds_bpermute_b32 v78, v8, v74
	ds_bpermute_b32 v79, v8, v75
	s_waitcnt lgkmcnt(3)
	v_add_f32_e32 v72, v72, v76
	s_waitcnt lgkmcnt(2)
	v_add_f32_e32 v73, v73, v77
	s_waitcnt lgkmcnt(1)
	v_add_f32_e32 v74, v74, v78
	s_waitcnt lgkmcnt(0)
	v_add_f32_e32 v75, v75, v79
	ds_bpermute_b32 v76, v9, v72
	ds_bpermute_b32 v77, v9, v73
	ds_bpermute_b32 v78, v9, v74
	ds_bpermute_b32 v79, v9, v75
	s_waitcnt lgkmcnt(3)
	v_add_f32_e32 v72, v72, v76
	s_waitcnt lgkmcnt(2)
	v_add_f32_e32 v73, v73, v77
	s_waitcnt lgkmcnt(1)
	v_add_f32_e32 v74, v74, v78
	s_waitcnt lgkmcnt(0)
	v_add_f32_e32 v75, v75, v79
	ds_bpermute_b32 v76, v10, v72
	ds_bpermute_b32 v77, v10, v73
	ds_bpermute_b32 v78, v10, v74
	ds_bpermute_b32 v79, v10, v75
	s_waitcnt lgkmcnt(3)
	v_add_f32_e32 v72, v72, v76
	s_waitcnt lgkmcnt(2)
	v_add_f32_e32 v73, v73, v77
	s_waitcnt lgkmcnt(1)
	v_add_f32_e32 v74, v74, v78
	s_waitcnt lgkmcnt(0)
	v_add_f32_e32 v75, v75, v79
	ds_bpermute_b32 v76, v11, v72
	ds_bpermute_b32 v77, v11, v73
	ds_bpermute_b32 v78, v11, v74
	ds_bpermute_b32 v79, v11, v75
	s_waitcnt lgkmcnt(3)
	v_add_f32_e32 v72, v72, v76
	s_waitcnt lgkmcnt(2)
	v_add_f32_e32 v73, v73, v77
	s_waitcnt lgkmcnt(1)
	v_add_f32_e32 v74, v74, v78
	s_waitcnt lgkmcnt(0)
	v_add_f32_e32 v75, v75, v79
	ds_bpermute_b32 v76, v12, v72
	ds_bpermute_b32 v77, v12, v73
	ds_bpermute_b32 v78, v12, v74
	ds_bpermute_b32 v79, v12, v75
	s_waitcnt lgkmcnt(3)
	v_add_f32_e32 v72, v72, v76
	s_waitcnt lgkmcnt(2)
	v_add_f32_e32 v73, v73, v77
	s_waitcnt lgkmcnt(1)
	v_add_f32_e32 v74, v74, v78
	s_waitcnt lgkmcnt(0)
	v_add_f32_e32 v75, v75, v79
	ds_bpermute_b32 v76, v13, v72
	ds_bpermute_b32 v77, v13, v73
	ds_bpermute_b32 v78, v13, v74
	ds_bpermute_b32 v79, v13, v75
	s_waitcnt lgkmcnt(3)
	v_add_f32_e32 v72, v72, v76
	s_waitcnt lgkmcnt(2)
	v_add_f32_e32 v73, v73, v77
	s_waitcnt lgkmcnt(1)
	v_add_f32_e32 v74, v74, v78
	s_waitcnt lgkmcnt(0)
	v_add_f32_e32 v75, v75, v79
	v_fmamk_f32 v80, v72, 0x3c000000, v14
	v_mul_f32_e32 v76, 0x4b800000, v80
	v_cmp_gt_f32_e32 vcc, s14, v80
	s_nop 1
	v_cndmask_b32_e32 v80, v80, v76, vcc
	v_rsq_f32_e32 v80, v80
	s_nop 0
	v_mul_f32_e32 v76, 0x45800000, v80
	v_cndmask_b32_e32 v80, v80, v76, vcc
	v_mul_f32_e32 v64, v64, v80
	v_mul_f32_e32 v68, v68, v80
	v_mul_f32_e32 v64, v2, v64
	v_mul_f32_e32 v68, v3, v68
	v_lshlrev_b32_e32 v76, 16, v136
	v_and_b32_e32 v72, 0xffff0000, v136
	v_mul_f32_e32 v64, v64, v76
	v_mul_f32_e32 v68, v68, v72
	v_cvt_pk_bf16_f32 v64, v64, v68
	global_store_dword v[98:99], v64, off
	v_fmamk_f32 v81, v73, 0x3c000000, v14
	v_mul_f32_e32 v77, 0x4b800000, v81
	v_cmp_gt_f32_e32 vcc, s14, v81
	s_nop 1
	v_cndmask_b32_e32 v81, v81, v77, vcc
	v_rsq_f32_e32 v81, v81
	s_nop 0
	v_mul_f32_e32 v77, 0x45800000, v81
	v_cndmask_b32_e32 v81, v81, v77, vcc
	v_mul_f32_e32 v65, v65, v81
	v_mul_f32_e32 v69, v69, v81
	v_mul_f32_e32 v65, v2, v65
	v_mul_f32_e32 v69, v3, v69
	v_lshlrev_b32_e32 v77, 16, v137
	v_and_b32_e32 v73, 0xffff0000, v137
	v_mul_f32_e32 v65, v65, v77
	v_mul_f32_e32 v69, v69, v73
	v_cvt_pk_bf16_f32 v65, v65, v69
	global_store_dword v[98:99], v65, off offset:256
	v_fmamk_f32 v82, v74, 0x3c000000, v14
	v_mul_f32_e32 v78, 0x4b800000, v82
	v_cmp_gt_f32_e32 vcc, s14, v82
	s_nop 1
	v_cndmask_b32_e32 v82, v82, v78, vcc
	v_rsq_f32_e32 v82, v82
	s_nop 0
	v_mul_f32_e32 v78, 0x45800000, v82
	v_cndmask_b32_e32 v82, v82, v78, vcc
	v_mul_f32_e32 v66, v66, v82
	v_mul_f32_e32 v70, v70, v82
	v_mul_f32_e32 v66, v2, v66
	v_mul_f32_e32 v70, v3, v70
	v_lshlrev_b32_e32 v78, 16, v138
	v_and_b32_e32 v74, 0xffff0000, v138
	v_mul_f32_e32 v66, v66, v78
	v_mul_f32_e32 v70, v70, v74
	v_cvt_pk_bf16_f32 v66, v66, v70
	global_store_dword v[98:99], v66, off offset:512
	v_fmamk_f32 v83, v75, 0x3c000000, v14
	v_mul_f32_e32 v79, 0x4b800000, v83
	v_cmp_gt_f32_e32 vcc, s14, v83
	s_nop 1
	v_cndmask_b32_e32 v83, v83, v79, vcc
	v_rsq_f32_e32 v83, v83
	s_nop 0
	v_mul_f32_e32 v79, 0x45800000, v83
	v_cndmask_b32_e32 v83, v83, v79, vcc
	v_mul_f32_e32 v67, v67, v83
	v_mul_f32_e32 v71, v71, v83
	v_mul_f32_e32 v67, v2, v67
	v_mul_f32_e32 v71, v3, v71
	v_lshlrev_b32_e32 v79, 16, v139
	v_and_b32_e32 v75, 0xffff0000, v139
	v_mul_f32_e32 v67, v67, v79
	v_mul_f32_e32 v71, v71, v75
	v_cvt_pk_bf16_f32 v67, v67, v71
	global_store_dword v[98:99], v67, off offset:768
	v_lshl_add_u64 v[98:99], v[98:99], 0, s[16:17]
	global_load_dword v128, v[92:93], off
	global_load_dword v129, v[92:93], off offset:256
	global_load_dword v130, v[92:93], off offset:512
	global_load_dword v131, v[92:93], off offset:768
	global_load_dword v132, v[94:95], off
	global_load_dword v133, v[94:95], off offset:256
	global_load_dword v134, v[94:95], off offset:512
	global_load_dword v135, v[94:95], off offset:768
	global_load_dword v136, v[96:97], off
	global_load_dword v137, v[96:97], off offset:256
	global_load_dword v138, v[96:97], off offset:512
	global_load_dword v139, v[96:97], off offset:768
	v_lshl_add_u64 v[92:93], v[92:93], 0, s[10:11]
	v_lshl_add_u64 v[94:95], v[94:95], 0, s[10:11]
	v_lshl_add_u64 v[96:97], v[96:97], 0, s[10:11]
	s_waitcnt vmcnt(48)
; DI unsigned cvt_pk_bf16(float lo, float hi) { unsigned r; asm("v_cvt_pk_bf16_f32 %0, %1, %2" : "=v"(r) : "v"(lo), "v"(hi)); return r; }
; DI void phase_combine(const Params& p) {
;     ...
;     for (int hh = 0; hh < 4; ++hh) { const size_t idx = ((size_t)tok * 512 + hh * 128 + lane * 2) >> 1; a[hh] = ofw[idx]; b[hh] = obw[idx]; g[hh] = GH[idx]; }
; #pragma unroll
;     for (int hh = 0; hh < 4; ++hh) {
;       const float o0 = __uint_as_float(a[hh] << 16) + __uint_as_float(b[hh] << 16), o1 = __uint_as_float(a[hh] & 0xffff0000u) + __uint_as_float(b[hh] & 0xffff0000u);
;       const float ss = wave_sum(o0 * o0 + o1 * o1);
;       const float rstd = rsqrtf(ss * (1.f / 128.f) + EPSN);
;       const float g0 = __uint_as_float(g[hh] << 16), g1 = __uint_as_float(g[hh] & 0xffff0000u);
;       *(unsigned*)(OC + (size_t)tok * 1024 + 512 + hh * 128 + lane * 2) = cvt_pk_bf16(o0 * rstd * w0 * g0, o1 * rstd * w1 * g1);
;     }
	v_lshlrev_b32_e32 v64, 16, v140
	v_lshlrev_b32_e32 v76, 16, v144
	v_and_b32_e32 v68, 0xffff0000, v140
	v_and_b32_e32 v80, 0xffff0000, v144
	v_add_f32_e32 v64, v64, v76
	v_add_f32_e32 v68, v68, v80
	v_mul_f32_e32 v72, v64, v64
	v_mul_f32_e32 v76, v68, v68
	v_add_f32_e32 v72, v72, v76
	v_lshlrev_b32_e32 v65, 16, v141
	v_lshlrev_b32_e32 v77, 16, v145
	v_and_b32_e32 v69, 0xffff0000, v141
	v_and_b32_e32 v81, 0xffff0000, v145
	v_add_f32_e32 v65, v65, v77
	v_add_f32_e32 v69, v69, v81
	v_mul_f32_e32 v73, v65, v65
	v_mul_f32_e32 v77, v69, v69
	v_add_f32_e32 v73, v73, v77
	v_lshlrev_b32_e32 v66, 16, v142
	v_lshlrev_b32_e32 v78, 16, v146
	v_and_b32_e32 v70, 0xffff0000, v142
	v_and_b32_e32 v82, 0xffff0000, v146
	v_add_f32_e32 v66, v66, v78
	v_add_f32_e32 v70, v70, v82
	v_mul_f32_e32 v74, v66, v66
	v_mul_f32_e32 v78, v70, v70
	v_add_f32_e32 v74, v74, v78
	v_lshlrev_b32_e32 v67, 16, v143
	v_lshlrev_b32_e32 v79, 16, v147
	v_and_b32_e32 v71, 0xffff0000, v143
	v_and_b32_e32 v83, 0xffff0000, v147
	v_add_f32_e32 v67, v67, v79
	v_add_f32_e32 v71, v71, v83
	v_mul_f32_e32 v75, v67, v67
	v_mul_f32_e32 v79, v71, v71
	v_add_f32_e32 v75, v75, v79
	ds_bpermute_b32 v76, v8, v72
	ds_bpermute_b32 v77, v8, v73
	ds_bpermute_b32 v78, v8, v74
	ds_bpermute_b32 v79, v8, v75
	s_waitcnt lgkmcnt(3)
	v_add_f32_e32 v72, v72, v76
	s_waitcnt lgkmcnt(2)
	v_add_f32_e32 v73, v73, v77
	s_waitcnt lgkmcnt(1)
	v_add_f32_e32 v74, v74, v78
	s_waitcnt lgkmcnt(0)
	v_add_f32_e32 v75, v75, v79
	ds_bpermute_b32 v76, v9, v72
	ds_bpermute_b32 v77, v9, v73
	ds_bpermute_b32 v78, v9, v74
	ds_bpermute_b32 v79, v9, v75
	s_waitcnt lgkmcnt(3)
	v_add_f32_e32 v72, v72, v76
	s_waitcnt lgkmcnt(2)
	v_add_f32_e32 v73, v73, v77
	s_waitcnt lgkmcnt(1)
	v_add_f32_e32 v74, v74, v78
	s_waitcnt lgkmcnt(0)
	v_add_f32_e32 v75, v75, v79
	ds_bpermute_b32 v76, v10, v72
	ds_bpermute_b32 v77, v10, v73
	ds_bpermute_b32 v78, v10, v74
	ds_bpermute_b32 v79, v10, v75
	s_waitcnt lgkmcnt(3)
	v_add_f32_e32 v72, v72, v76
	s_waitcnt lgkmcnt(2)
	v_add_f32_e32 v73, v73, v77
	s_waitcnt lgkmcnt(1)
	v_add_f32_e32 v74, v74, v78
	s_waitcnt lgkmcnt(0)
	v_add_f32_e32 v75, v75, v79
	ds_bpermute_b32 v76, v11, v72
	ds_bpermute_b32 v77, v11, v73
	ds_bpermute_b32 v78, v11, v74
	ds_bpermute_b32 v79, v11, v75
	s_waitcnt lgkmcnt(3)
	v_add_f32_e32 v72, v72, v76
	s_waitcnt lgkmcnt(2)
	v_add_f32_e32 v73, v73, v77
	s_waitcnt lgkmcnt(1)
	v_add_f32_e32 v74, v74, v78
	s_waitcnt lgkmcnt(0)
	v_add_f32_e32 v75, v75, v79
	ds_bpermute_b32 v76, v12, v72
	ds_bpermute_b32 v77, v12, v73
	ds_bpermute_b32 v78, v12, v74
	ds_bpermute_b32 v79, v12, v75
	s_waitcnt lgkmcnt(3)
	v_add_f32_e32 v72, v72, v76
	s_waitcnt lgkmcnt(2)
	v_add_f32_e32 v73, v73, v77
	s_waitcnt lgkmcnt(1)
	v_add_f32_e32 v74, v74, v78
	s_waitcnt lgkmcnt(0)
	v_add_f32_e32 v75, v75, v79
	ds_bpermute_b32 v76, v13, v72
	ds_bpermute_b32 v77, v13, v73
	ds_bpermute_b32 v78, v13, v74
	ds_bpermute_b32 v79, v13, v75
	s_waitcnt lgkmcnt(3)
	v_add_f32_e32 v72, v72, v76
	s_waitcnt lgkmcnt(2)
	v_add_f32_e32 v73, v73, v77
	s_waitcnt lgkmcnt(1)
	v_add_f32_e32 v74, v74, v78
	s_waitcnt lgkmcnt(0)
	v_add_f32_e32 v75, v75, v79
	v_fmamk_f32 v80, v72, 0x3c000000, v14
	v_mul_f32_e32 v76, 0x4b800000, v80
	v_cmp_gt_f32_e32 vcc, s14, v80
	s_nop 1
	v_cndmask_b32_e32 v80, v80, v76, vcc
	v_rsq_f32_e32 v80, v80
	s_nop 0
	v_mul_f32_e32 v76, 0x45800000, v80
	v_cndmask_b32_e32 v80, v80, v76, vcc
	v_mul_f32_e32 v64, v64, v80
	v_mul_f32_e32 v68, v68, v80
	v_mul_f32_e32 v64, v2, v64
	v_mul_f32_e32 v68, v3, v68
	v_lshlrev_b32_e32 v76, 16, v148
	v_and_b32_e32 v72, 0xffff0000, v148
	v_mul_f32_e32 v64, v64, v76
	v_mul_f32_e32 v68, v68, v72
	v_cvt_pk_bf16_f32 v64, v64, v68
	global_store_dword v[98:99], v64, off
	v_fmamk_f32 v81, v73, 0x3c000000, v14
	v_mul_f32_e32 v77, 0x4b800000, v81
	v_cmp_gt_f32_e32 vcc, s14, v81
	s_nop 1
	v_cndmask_b32_e32 v81, v81, v77, vcc
	v_rsq_f32_e32 v81, v81
	s_nop 0
	v_mul_f32_e32 v77, 0x45800000, v81
	v_cndmask_b32_e32 v81, v81, v77, vcc
	v_mul_f32_e32 v65, v65, v81
	v_mul_f32_e32 v69, v69, v81
	v_mul_f32_e32 v65, v2, v65
	v_mul_f32_e32 v69, v3, v69
	v_lshlrev_b32_e32 v77, 16, v149
	v_and_b32_e32 v73, 0xffff0000, v149
	v_mul_f32_e32 v65, v65, v77
	v_mul_f32_e32 v69, v69, v73
	v_cvt_pk_bf16_f32 v65, v65, v69
	global_store_dword v[98:99], v65, off offset:256
	v_fmamk_f32 v82, v74, 0x3c000000, v14
	v_mul_f32_e32 v78, 0x4b800000, v82
	v_cmp_gt_f32_e32 vcc, s14, v82
	s_nop 1
	v_cndmask_b32_e32 v82, v82, v78, vcc
	v_rsq_f32_e32 v82, v82
	s_nop 0
	v_mul_f32_e32 v78, 0x45800000, v82
	v_cndmask_b32_e32 v82, v82, v78, vcc
	v_mul_f32_e32 v66, v66, v82
	v_mul_f32_e32 v70, v70, v82
	v_mul_f32_e32 v66, v2, v66
	v_mul_f32_e32 v70, v3, v70
	v_lshlrev_b32_e32 v78, 16, v150
	v_and_b32_e32 v74, 0xffff0000, v150
	v_mul_f32_e32 v66, v66, v78
	v_mul_f32_e32 v70, v70, v74
	v_cvt_pk_bf16_f32 v66, v66, v70
	global_store_dword v[98:99], v66, off offset:512
	v_fmamk_f32 v83, v75, 0x3c000000, v14
	v_mul_f32_e32 v79, 0x4b800000, v83
	v_cmp_gt_f32_e32 vcc, s14, v83
	s_nop 1
	v_cndmask_b32_e32 v83, v83, v79, vcc
	v_rsq_f32_e32 v83, v83
	s_nop 0
	v_mul_f32_e32 v79, 0x45800000, v83
	v_cndmask_b32_e32 v83, v83, v79, vcc
	v_mul_f32_e32 v67, v67, v83
	v_mul_f32_e32 v71, v71, v83
	v_mul_f32_e32 v67, v2, v67
	v_mul_f32_e32 v71, v3, v71
	v_lshlrev_b32_e32 v79, 16, v151
	v_and_b32_e32 v75, 0xffff0000, v151
	v_mul_f32_e32 v67, v67, v79
	v_mul_f32_e32 v71, v71, v75
	v_cvt_pk_bf16_f32 v67, v67, v71
	global_store_dword v[98:99], v67, off offset:768
	v_lshl_add_u64 v[98:99], v[98:99], 0, s[16:17]
	global_load_dword v140, v[92:93], off
	global_load_dword v141, v[92:93], off offset:256
	global_load_dword v142, v[92:93], off offset:512
	global_load_dword v143, v[92:93], off offset:768
	global_load_dword v144, v[94:95], off
	global_load_dword v145, v[94:95], off offset:256
	global_load_dword v146, v[94:95], off offset:512
	global_load_dword v147, v[94:95], off offset:768
	global_load_dword v148, v[96:97], off
	global_load_dword v149, v[96:97], off offset:256
	global_load_dword v150, v[96:97], off offset:512
	global_load_dword v151, v[96:97], off offset:768
	v_lshl_add_u64 v[92:93], v[92:93], 0, s[10:11]
	v_lshl_add_u64 v[94:95], v[94:95], 0, s[10:11]
	v_lshl_add_u64 v[96:97], v[96:97], 0, s[10:11]
	s_sub_i32 s98, s98, 1
	s_cmp_lg_u32 s98, 0
	s_cbranch_scc1 .Lcq_loop
; DI unsigned cvt_pk_bf16(float lo, float hi) { unsigned r; asm("v_cvt_pk_bf16_f32 %0, %1, %2" : "=v"(r) : "v"(lo), "v"(hi)); return r; }
; DI void phase_combine(const Params& p) {
;     ...
;     for (int hh = 0; hh < 4; ++hh) { const size_t idx = ((size_t)tok * 512 + hh * 128 + lane * 2) >> 1; a[hh] = ofw[idx]; b[hh] = obw[idx]; g[hh] = GH[idx]; }
; #pragma unroll
;     for (int hh = 0; hh < 4; ++hh) {
;       const float o0 = __uint_as_float(a[hh] << 16) + __uint_as_float(b[hh] << 16), o1 = __uint_as_float(a[hh] & 0xffff0000u) + __uint_as_float(b[hh] & 0xffff0000u);
;       const float ss = wave_sum(o0 * o0 + o1 * o1);
;       const float rstd = rsqrtf(ss * (1.f / 128.f) + EPSN);
;       const float g0 = __uint_as_float(g[hh] << 16), g1 = __uint_as_float(g[hh] & 0xffff0000u);
;       *(unsigned*)(OC + (size_t)tok * 1024 + 512 + hh * 128 + lane * 2) = cvt_pk_bf16(o0 * rstd * w0 * g0, o1 * rstd * w1 * g1);
;     }
	s_waitcnt vmcnt(48)
	v_lshlrev_b32_e32 v64, 16, v104
	v_lshlrev_b32_e32 v76, 16, v108
	v_and_b32_e32 v68, 0xffff0000, v104
	v_and_b32_e32 v80, 0xffff0000, v108
	v_add_f32_e32 v64, v64, v76
	v_add_f32_e32 v68, v68, v80
	v_mul_f32_e32 v72, v64, v64
	v_mul_f32_e32 v76, v68, v68
	v_add_f32_e32 v72, v72, v76
	v_lshlrev_b32_e32 v65, 16, v105
	v_lshlrev_b32_e32 v77, 16, v109
	v_and_b32_e32 v69, 0xffff0000, v105
	v_and_b32_e32 v81, 0xffff0000, v109
	v_add_f32_e32 v65, v65, v77
	v_add_f32_e32 v69, v69, v81
	v_mul_f32_e32 v73, v65, v65
	v_mul_f32_e32 v77, v69, v69
	v_add_f32_e32 v73, v73, v77
	v_lshlrev_b32_e32 v66, 16, v106
	v_lshlrev_b32_e32 v78, 16, v110
	v_and_b32_e32 v70, 0xffff0000, v106
	v_and_b32_e32 v82, 0xffff0000, v110
	v_add_f32_e32 v66, v66, v78
	v_add_f32_e32 v70, v70, v82
	v_mul_f32_e32 v74, v66, v66
	v_mul_f32_e32 v78, v70, v70
	v_add_f32_e32 v74, v74, v78
	v_lshlrev_b32_e32 v67, 16, v107
	v_lshlrev_b32_e32 v79, 16, v111
	v_and_b32_e32 v71, 0xffff0000, v107
	v_and_b32_e32 v83, 0xffff0000, v111
	v_add_f32_e32 v67, v67, v79
	v_add_f32_e32 v71, v71, v83
	v_mul_f32_e32 v75, v67, v67
	v_mul_f32_e32 v79, v71, v71
	v_add_f32_e32 v75, v75, v79
	ds_bpermute_b32 v76, v8, v72
	ds_bpermute_b32 v77, v8, v73
	ds_bpermute_b32 v78, v8, v74
	ds_bpermute_b32 v79, v8, v75
	s_waitcnt lgkmcnt(3)
	v_add_f32_e32 v72, v72, v76
	s_waitcnt lgkmcnt(2)
	v_add_f32_e32 v73, v73, v77
	s_waitcnt lgkmcnt(1)
	v_add_f32_e32 v74, v74, v78
	s_waitcnt lgkmcnt(0)
	v_add_f32_e32 v75, v75, v79
	ds_bpermute_b32 v76, v9, v72
	ds_bpermute_b32 v77, v9, v73
	ds_bpermute_b32 v78, v9, v74
	ds_bpermute_b32 v79, v9, v75
	s_waitcnt lgkmcnt(3)
	v_add_f32_e32 v72, v72, v76
	s_waitcnt lgkmcnt(2)
	v_add_f32_e32 v73, v73, v77
	s_waitcnt lgkmcnt(1)
	v_add_f32_e32 v74, v74, v78
	s_waitcnt lgkmcnt(0)
	v_add_f32_e32 v75, v75, v79
	ds_bpermute_b32 v76, v10, v72
	ds_bpermute_b32 v77, v10, v73
	ds_bpermute_b32 v78, v10, v74
	ds_bpermute_b32 v79, v10, v75
	s_waitcnt lgkmcnt(3)
	v_add_f32_e32 v72, v72, v76
	s_waitcnt lgkmcnt(2)
	v_add_f32_e32 v73, v73, v77
	s_waitcnt lgkmcnt(1)
	v_add_f32_e32 v74, v74, v78
	s_waitcnt lgkmcnt(0)
	v_add_f32_e32 v75, v75, v79
	ds_bpermute_b32 v76, v11, v72
	ds_bpermute_b32 v77, v11, v73
	ds_bpermute_b32 v78, v11, v74
	ds_bpermute_b32 v79, v11, v75
	s_waitcnt lgkmcnt(3)
	v_add_f32_e32 v72, v72, v76
	s_waitcnt lgkmcnt(2)
	v_add_f32_e32 v73, v73, v77
	s_waitcnt lgkmcnt(1)
	v_add_f32_e32 v74, v74, v78
	s_waitcnt lgkmcnt(0)
	v_add_f32_e32 v75, v75, v79
	ds_bpermute_b32 v76, v12, v72
	ds_bpermute_b32 v77, v12, v73
	ds_bpermute_b32 v78, v12, v74
	ds_bpermute_b32 v79, v12, v75
	s_waitcnt lgkmcnt(3)
	v_add_f32_e32 v72, v72, v76
	s_waitcnt lgkmcnt(2)
	v_add_f32_e32 v73, v73, v77
	s_waitcnt lgkmcnt(1)
	v_add_f32_e32 v74, v74, v78
	s_waitcnt lgkmcnt(0)
	v_add_f32_e32 v75, v75, v79
	ds_bpermute_b32 v76, v13, v72
	ds_bpermute_b32 v77, v13, v73
	ds_bpermute_b32 v78, v13, v74
	ds_bpermute_b32 v79, v13, v75
	s_waitcnt lgkmcnt(3)
	v_add_f32_e32 v72, v72, v76
	s_waitcnt lgkmcnt(2)
	v_add_f32_e32 v73, v73, v77
	s_waitcnt lgkmcnt(1)
	v_add_f32_e32 v74, v74, v78
	s_waitcnt lgkmcnt(0)
	v_add_f32_e32 v75, v75, v79
	v_fmamk_f32 v80, v72, 0x3c000000, v14
	v_mul_f32_e32 v76, 0x4b800000, v80
	v_cmp_gt_f32_e32 vcc, s14, v80
	s_nop 1
	v_cndmask_b32_e32 v80, v80, v76, vcc
	v_rsq_f32_e32 v80, v80
	s_nop 0
	v_mul_f32_e32 v76, 0x45800000, v80
	v_cndmask_b32_e32 v80, v80, v76, vcc
	v_mul_f32_e32 v64, v64, v80
	v_mul_f32_e32 v68, v68, v80
	v_mul_f32_e32 v64, v2, v64
	v_mul_f32_e32 v68, v3, v68
	v_lshlrev_b32_e32 v76, 16, v112
	v_and_b32_e32 v72, 0xffff0000, v112
	v_mul_f32_e32 v64, v64, v76
	v_mul_f32_e32 v68, v68, v72
	v_cvt_pk_bf16_f32 v64, v64, v68
	global_store_dword v[98:99], v64, off
	v_fmamk_f32 v81, v73, 0x3c000000, v14
	v_mul_f32_e32 v77, 0x4b800000, v81
	v_cmp_gt_f32_e32 vcc, s14, v81
	s_nop 1
	v_cndmask_b32_e32 v81, v81, v77, vcc
	v_rsq_f32_e32 v81, v81
	s_nop 0
	v_mul_f32_e32 v77, 0x45800000, v81
	v_cndmask_b32_e32 v81, v81, v77, vcc
	v_mul_f32_e32 v65, v65, v81
	v_mul_f32_e32 v69, v69, v81
	v_mul_f32_e32 v65, v2, v65
	v_mul_f32_e32 v69, v3, v69
	v_lshlrev_b32_e32 v77, 16, v113
	v_and_b32_e32 v73, 0xffff0000, v113
	v_mul_f32_e32 v65, v65, v77
	v_mul_f32_e32 v69, v69, v73
	v_cvt_pk_bf16_f32 v65, v65, v69
	global_store_dword v[98:99], v65, off offset:256
	v_fmamk_f32 v82, v74, 0x3c000000, v14
	v_mul_f32_e32 v78, 0x4b800000, v82
	v_cmp_gt_f32_e32 vcc, s14, v82
	s_nop 1
	v_cndmask_b32_e32 v82, v82, v78, vcc
	v_rsq_f32_e32 v82, v82
	s_nop 0
	v_mul_f32_e32 v78, 0x45800000, v82
	v_cndmask_b32_e32 v82, v82, v78, vcc
	v_mul_f32_e32 v66, v66, v82
	v_mul_f32_e32 v70, v70, v82
	v_mul_f32_e32 v66, v2, v66
	v_mul_f32_e32 v70, v3, v70
	v_lshlrev_b32_e32 v78, 16, v114
	v_and_b32_e32 v74, 0xffff0000, v114
	v_mul_f32_e32 v66, v66, v78
	v_mul_f32_e32 v70, v70, v74
	v_cvt_pk_bf16_f32 v66, v66, v70
	global_store_dword v[98:99], v66, off offset:512
	v_fmamk_f32 v83, v75, 0x3c000000, v14
	v_mul_f32_e32 v79, 0x4b800000, v83
	v_cmp_gt_f32_e32 vcc, s14, v83
	s_nop 1
	v_cndmask_b32_e32 v83, v83, v79, vcc
	v_rsq_f32_e32 v83, v83
	s_nop 0
	v_mul_f32_e32 v79, 0x45800000, v83
	v_cndmask_b32_e32 v83, v83, v79, vcc
	v_mul_f32_e32 v67, v67, v83
	v_mul_f32_e32 v71, v71, v83
	v_mul_f32_e32 v67, v2, v67
	v_mul_f32_e32 v71, v3, v71
	v_lshlrev_b32_e32 v79, 16, v115
	v_and_b32_e32 v75, 0xffff0000, v115
	v_mul_f32_e32 v67, v67, v79
	v_mul_f32_e32 v71, v71, v75
	v_cvt_pk_bf16_f32 v67, v67, v71
	global_store_dword v[98:99], v67, off offset:768
	v_lshl_add_u64 v[98:99], v[98:99], 0, s[16:17]
	s_waitcnt vmcnt(36)
; DI unsigned cvt_pk_bf16(float lo, float hi) { unsigned r; asm("v_cvt_pk_bf16_f32 %0, %1, %2" : "=v"(r) : "v"(lo), "v"(hi)); return r; }
; DI void phase_combine(const Params& p) {
;     ...
;     for (int hh = 0; hh < 4; ++hh) { const size_t idx = ((size_t)tok * 512 + hh * 128 + lane * 2) >> 1; a[hh] = ofw[idx]; b[hh] = obw[idx]; g[hh] = GH[idx]; }
; #pragma unroll
;     for (int hh = 0; hh < 4; ++hh) {
;       const float o0 = __uint_as_float(a[hh] << 16) + __uint_as_float(b[hh] << 16), o1 = __uint_as_float(a[hh] & 0xffff0000u) + __uint_as_float(b[hh] & 0xffff0000u);
;       const float ss = wave_sum(o0 * o0 + o1 * o1);
;       const float rstd = rsqrtf(ss * (1.f / 128.f) + EPSN);
;       const float g0 = __uint_as_float(g[hh] << 16), g1 = __uint_as_float(g[hh] & 0xffff0000u);
;       *(unsigned*)(OC + (size_t)tok * 1024 + 512 + hh * 128 + lane * 2) = cvt_pk_bf16(o0 * rstd * w0 * g0, o1 * rstd * w1 * g1);
;     }
	v_lshlrev_b32_e32 v64, 16, v116
	v_lshlrev_b32_e32 v76, 16, v120
	v_and_b32_e32 v68, 0xffff0000, v116
	v_and_b32_e32 v80, 0xffff0000, v120
	v_add_f32_e32 v64, v64, v76
	v_add_f32_e32 v68, v68, v80
	v_mul_f32_e32 v72, v64, v64
	v_mul_f32_e32 v76, v68, v68
	v_add_f32_e32 v72, v72, v76
	v_lshlrev_b32_e32 v65, 16, v117
	v_lshlrev_b32_e32 v77, 16, v121
	v_and_b32_e32 v69, 0xffff0000, v117
	v_and_b32_e32 v81, 0xffff0000, v121
	v_add_f32_e32 v65, v65, v77
	v_add_f32_e32 v69, v69, v81
	v_mul_f32_e32 v73, v65, v65
	v_mul_f32_e32 v77, v69, v69
	v_add_f32_e32 v73, v73, v77
	v_lshlrev_b32_e32 v66, 16, v118
	v_lshlrev_b32_e32 v78, 16, v122
	v_and_b32_e32 v70, 0xffff0000, v118
	v_and_b32_e32 v82, 0xffff0000, v122
	v_add_f32_e32 v66, v66, v78
	v_add_f32_e32 v70, v70, v82
	v_mul_f32_e32 v74, v66, v66
	v_mul_f32_e32 v78, v70, v70
	v_add_f32_e32 v74, v74, v78
	v_lshlrev_b32_e32 v67, 16, v119
	v_lshlrev_b32_e32 v79, 16, v123
	v_and_b32_e32 v71, 0xffff0000, v119
	v_and_b32_e32 v83, 0xffff0000, v123
	v_add_f32_e32 v67, v67, v79
	v_add_f32_e32 v71, v71, v83
	v_mul_f32_e32 v75, v67, v67
	v_mul_f32_e32 v79, v71, v71
	v_add_f32_e32 v75, v75, v79
	ds_bpermute_b32 v76, v8, v72
	ds_bpermute_b32 v77, v8, v73
	ds_bpermute_b32 v78, v8, v74
	ds_bpermute_b32 v79, v8, v75
	s_waitcnt lgkmcnt(3)
	v_add_f32_e32 v72, v72, v76
	s_waitcnt lgkmcnt(2)
	v_add_f32_e32 v73, v73, v77
	s_waitcnt lgkmcnt(1)
	v_add_f32_e32 v74, v74, v78
	s_waitcnt lgkmcnt(0)
	v_add_f32_e32 v75, v75, v79
	ds_bpermute_b32 v76, v9, v72
	ds_bpermute_b32 v77, v9, v73
	ds_bpermute_b32 v78, v9, v74
	ds_bpermute_b32 v79, v9, v75
	s_waitcnt lgkmcnt(3)
	v_add_f32_e32 v72, v72, v76
	s_waitcnt lgkmcnt(2)
	v_add_f32_e32 v73, v73, v77
	s_waitcnt lgkmcnt(1)
	v_add_f32_e32 v74, v74, v78
	s_waitcnt lgkmcnt(0)
	v_add_f32_e32 v75, v75, v79
	ds_bpermute_b32 v76, v10, v72
	ds_bpermute_b32 v77, v10, v73
	ds_bpermute_b32 v78, v10, v74
	ds_bpermute_b32 v79, v10, v75
	s_waitcnt lgkmcnt(3)
	v_add_f32_e32 v72, v72, v76
	s_waitcnt lgkmcnt(2)
	v_add_f32_e32 v73, v73, v77
	s_waitcnt lgkmcnt(1)
	v_add_f32_e32 v74, v74, v78
	s_waitcnt lgkmcnt(0)
	v_add_f32_e32 v75, v75, v79
	ds_bpermute_b32 v76, v11, v72
	ds_bpermute_b32 v77, v11, v73
	ds_bpermute_b32 v78, v11, v74
	ds_bpermute_b32 v79, v11, v75
	s_waitcnt lgkmcnt(3)
	v_add_f32_e32 v72, v72, v76
	s_waitcnt lgkmcnt(2)
	v_add_f32_e32 v73, v73, v77
	s_waitcnt lgkmcnt(1)
	v_add_f32_e32 v74, v74, v78
	s_waitcnt lgkmcnt(0)
	v_add_f32_e32 v75, v75, v79
	ds_bpermute_b32 v76, v12, v72
	ds_bpermute_b32 v77, v12, v73
	ds_bpermute_b32 v78, v12, v74
	ds_bpermute_b32 v79, v12, v75
	s_waitcnt lgkmcnt(3)
	v_add_f32_e32 v72, v72, v76
	s_waitcnt lgkmcnt(2)
	v_add_f32_e32 v73, v73, v77
	s_waitcnt lgkmcnt(1)
	v_add_f32_e32 v74, v74, v78
	s_waitcnt lgkmcnt(0)
	v_add_f32_e32 v75, v75, v79
	ds_bpermute_b32 v76, v13, v72
	ds_bpermute_b32 v77, v13, v73
	ds_bpermute_b32 v78, v13, v74
	ds_bpermute_b32 v79, v13, v75
	s_waitcnt lgkmcnt(3)
	v_add_f32_e32 v72, v72, v76
	s_waitcnt lgkmcnt(2)
	v_add_f32_e32 v73, v73, v77
	s_waitcnt lgkmcnt(1)
	v_add_f32_e32 v74, v74, v78
	s_waitcnt lgkmcnt(0)
	v_add_f32_e32 v75, v75, v79
	v_fmamk_f32 v80, v72, 0x3c000000, v14
	v_mul_f32_e32 v76, 0x4b800000, v80
	v_cmp_gt_f32_e32 vcc, s14, v80
	s_nop 1
	v_cndmask_b32_e32 v80, v80, v76, vcc
	v_rsq_f32_e32 v80, v80
	s_nop 0
	v_mul_f32_e32 v76, 0x45800000, v80
	v_cndmask_b32_e32 v80, v80, v76, vcc
	v_mul_f32_e32 v64, v64, v80
	v_mul_f32_e32 v68, v68, v80
	v_mul_f32_e32 v64, v2, v64
	v_mul_f32_e32 v68, v3, v68
	v_lshlrev_b32_e32 v76, 16, v124
	v_and_b32_e32 v72, 0xffff0000, v124
	v_mul_f32_e32 v64, v64, v76
	v_mul_f32_e32 v68, v68, v72
	v_cvt_pk_bf16_f32 v64, v64, v68
	global_store_dword v[98:99], v64, off
	v_fmamk_f32 v81, v73, 0x3c000000, v14
	v_mul_f32_e32 v77, 0x4b800000, v81
	v_cmp_gt_f32_e32 vcc, s14, v81
	s_nop 1
	v_cndmask_b32_e32 v81, v81, v77, vcc
	v_rsq_f32_e32 v81, v81
	s_nop 0
	v_mul_f32_e32 v77, 0x45800000, v81
	v_cndmask_b32_e32 v81, v81, v77, vcc
	v_mul_f32_e32 v65, v65, v81
	v_mul_f32_e32 v69, v69, v81
	v_mul_f32_e32 v65, v2, v65
	v_mul_f32_e32 v69, v3, v69
	v_lshlrev_b32_e32 v77, 16, v125
	v_and_b32_e32 v73, 0xffff0000, v125
	v_mul_f32_e32 v65, v65, v77
	v_mul_f32_e32 v69, v69, v73
	v_cvt_pk_bf16_f32 v65, v65, v69
	global_store_dword v[98:99], v65, off offset:256
	v_fmamk_f32 v82, v74, 0x3c000000, v14
	v_mul_f32_e32 v78, 0x4b800000, v82
	v_cmp_gt_f32_e32 vcc, s14, v82
	s_nop 1
	v_cndmask_b32_e32 v82, v82, v78, vcc
	v_rsq_f32_e32 v82, v82
	s_nop 0
	v_mul_f32_e32 v78, 0x45800000, v82
	v_cndmask_b32_e32 v82, v82, v78, vcc
	v_mul_f32_e32 v66, v66, v82
	v_mul_f32_e32 v70, v70, v82
	v_mul_f32_e32 v66, v2, v66
	v_mul_f32_e32 v70, v3, v70
	v_lshlrev_b32_e32 v78, 16, v126
	v_and_b32_e32 v74, 0xffff0000, v126
	v_mul_f32_e32 v66, v66, v78
	v_mul_f32_e32 v70, v70, v74
	v_cvt_pk_bf16_f32 v66, v66, v70
	global_store_dword v[98:99], v66, off offset:512
	v_fmamk_f32 v83, v75, 0x3c000000, v14
	v_mul_f32_e32 v79, 0x4b800000, v83
	v_cmp_gt_f32_e32 vcc, s14, v83
	s_nop 1
	v_cndmask_b32_e32 v83, v83, v79, vcc
	v_rsq_f32_e32 v83, v83
	s_nop 0
	v_mul_f32_e32 v79, 0x45800000, v83
	v_cndmask_b32_e32 v83, v83, v79, vcc
	v_mul_f32_e32 v67, v67, v83
	v_mul_f32_e32 v71, v71, v83
	v_mul_f32_e32 v67, v2, v67
	v_mul_f32_e32 v71, v3, v71
	v_lshlrev_b32_e32 v79, 16, v127
	v_and_b32_e32 v75, 0xffff0000, v127
	v_mul_f32_e32 v67, v67, v79
	v_mul_f32_e32 v71, v71, v75
	v_cvt_pk_bf16_f32 v67, v67, v71
	global_store_dword v[98:99], v67, off offset:768
	v_lshl_add_u64 v[98:99], v[98:99], 0, s[16:17]
	s_waitcnt vmcnt(24)
; DI unsigned cvt_pk_bf16(float lo, float hi) { unsigned r; asm("v_cvt_pk_bf16_f32 %0, %1, %2" : "=v"(r) : "v"(lo), "v"(hi)); return r; }
; DI void phase_combine(const Params& p) {
;     ...
;     for (int hh = 0; hh < 4; ++hh) { const size_t idx = ((size_t)tok * 512 + hh * 128 + lane * 2) >> 1; a[hh] = ofw[idx]; b[hh] = obw[idx]; g[hh] = GH[idx]; }
; #pragma unroll
;     for (int hh = 0; hh < 4; ++hh) {
;       const float o0 = __uint_as_float(a[hh] << 16) + __uint_as_float(b[hh] << 16), o1 = __uint_as_float(a[hh] & 0xffff0000u) + __uint_as_float(b[hh] & 0xffff0000u);
;       const float ss = wave_sum(o0 * o0 + o1 * o1);
;       const float rstd = rsqrtf(ss * (1.f / 128.f) + EPSN);
;       const float g0 = __uint_as_float(g[hh] << 16), g1 = __uint_as_float(g[hh] & 0xffff0000u);
;       *(unsigned*)(OC + (size_t)tok * 1024 + 512 + hh * 128 + lane * 2) = cvt_pk_bf16(o0 * rstd * w0 * g0, o1 * rstd * w1 * g1);
;     }
	v_lshlrev_b32_e32 v64, 16, v128
	v_lshlrev_b32_e32 v76, 16, v132
	v_and_b32_e32 v68, 0xffff0000, v128
	v_and_b32_e32 v80, 0xffff0000, v132
	v_add_f32_e32 v64, v64, v76
	v_add_f32_e32 v68, v68, v80
	v_mul_f32_e32 v72, v64, v64
	v_mul_f32_e32 v76, v68, v68
	v_add_f32_e32 v72, v72, v76
	v_lshlrev_b32_e32 v65, 16, v129
	v_lshlrev_b32_e32 v77, 16, v133
	v_and_b32_e32 v69, 0xffff0000, v129
	v_and_b32_e32 v81, 0xffff0000, v133
	v_add_f32_e32 v65, v65, v77
	v_add_f32_e32 v69, v69, v81
	v_mul_f32_e32 v73, v65, v65
	v_mul_f32_e32 v77, v69, v69
	v_add_f32_e32 v73, v73, v77
	v_lshlrev_b32_e32 v66, 16, v130
	v_lshlrev_b32_e32 v78, 16, v134
	v_and_b32_e32 v70, 0xffff0000, v130
	v_and_b32_e32 v82, 0xffff0000, v134
	v_add_f32_e32 v66, v66, v78
	v_add_f32_e32 v70, v70, v82
	v_mul_f32_e32 v74, v66, v66
	v_mul_f32_e32 v78, v70, v70
	v_add_f32_e32 v74, v74, v78
	v_lshlrev_b32_e32 v67, 16, v131
	v_lshlrev_b32_e32 v79, 16, v135
	v_and_b32_e32 v71, 0xffff0000, v131
	v_and_b32_e32 v83, 0xffff0000, v135
	v_add_f32_e32 v67, v67, v79
	v_add_f32_e32 v71, v71, v83
	v_mul_f32_e32 v75, v67, v67
	v_mul_f32_e32 v79, v71, v71
	v_add_f32_e32 v75, v75, v79
	ds_bpermute_b32 v76, v8, v72
	ds_bpermute_b32 v77, v8, v73
	ds_bpermute_b32 v78, v8, v74
	ds_bpermute_b32 v79, v8, v75
	s_waitcnt lgkmcnt(3)
	v_add_f32_e32 v72, v72, v76
	s_waitcnt lgkmcnt(2)
	v_add_f32_e32 v73, v73, v77
	s_waitcnt lgkmcnt(1)
	v_add_f32_e32 v74, v74, v78
	s_waitcnt lgkmcnt(0)
	v_add_f32_e32 v75, v75, v79
	ds_bpermute_b32 v76, v9, v72
	ds_bpermute_b32 v77, v9, v73
	ds_bpermute_b32 v78, v9, v74
	ds_bpermute_b32 v79, v9, v75
	s_waitcnt lgkmcnt(3)
	v_add_f32_e32 v72, v72, v76
	s_waitcnt lgkmcnt(2)
	v_add_f32_e32 v73, v73, v77
	s_waitcnt lgkmcnt(1)
	v_add_f32_e32 v74, v74, v78
	s_waitcnt lgkmcnt(0)
	v_add_f32_e32 v75, v75, v79
	ds_bpermute_b32 v76, v10, v72
	ds_bpermute_b32 v77, v10, v73
	ds_bpermute_b32 v78, v10, v74
	ds_bpermute_b32 v79, v10, v75
	s_waitcnt lgkmcnt(3)
	v_add_f32_e32 v72, v72, v76
	s_waitcnt lgkmcnt(2)
	v_add_f32_e32 v73, v73, v77
	s_waitcnt lgkmcnt(1)
	v_add_f32_e32 v74, v74, v78
	s_waitcnt lgkmcnt(0)
	v_add_f32_e32 v75, v75, v79
	ds_bpermute_b32 v76, v11, v72
	ds_bpermute_b32 v77, v11, v73
	ds_bpermute_b32 v78, v11, v74
	ds_bpermute_b32 v79, v11, v75
	s_waitcnt lgkmcnt(3)
	v_add_f32_e32 v72, v72, v76
	s_waitcnt lgkmcnt(2)
	v_add_f32_e32 v73, v73, v77
	s_waitcnt lgkmcnt(1)
	v_add_f32_e32 v74, v74, v78
	s_waitcnt lgkmcnt(0)
	v_add_f32_e32 v75, v75, v79
	ds_bpermute_b32 v76, v12, v72
	ds_bpermute_b32 v77, v12, v73
	ds_bpermute_b32 v78, v12, v74
	ds_bpermute_b32 v79, v12, v75
	s_waitcnt lgkmcnt(3)
	v_add_f32_e32 v72, v72, v76
	s_waitcnt lgkmcnt(2)
	v_add_f32_e32 v73, v73, v77
	s_waitcnt lgkmcnt(1)
	v_add_f32_e32 v74, v74, v78
	s_waitcnt lgkmcnt(0)
	v_add_f32_e32 v75, v75, v79
	ds_bpermute_b32 v76, v13, v72
	ds_bpermute_b32 v77, v13, v73
	ds_bpermute_b32 v78, v13, v74
	ds_bpermute_b32 v79, v13, v75
	s_waitcnt lgkmcnt(3)
	v_add_f32_e32 v72, v72, v76
	s_waitcnt lgkmcnt(2)
	v_add_f32_e32 v73, v73, v77
	s_waitcnt lgkmcnt(1)
	v_add_f32_e32 v74, v74, v78
	s_waitcnt lgkmcnt(0)
	v_add_f32_e32 v75, v75, v79
	v_fmamk_f32 v80, v72, 0x3c000000, v14
	v_mul_f32_e32 v76, 0x4b800000, v80
	v_cmp_gt_f32_e32 vcc, s14, v80
	s_nop 1
	v_cndmask_b32_e32 v80, v80, v76, vcc
	v_rsq_f32_e32 v80, v80
	s_nop 0
	v_mul_f32_e32 v76, 0x45800000, v80
	v_cndmask_b32_e32 v80, v80, v76, vcc
	v_mul_f32_e32 v64, v64, v80
	v_mul_f32_e32 v68, v68, v80
	v_mul_f32_e32 v64, v2, v64
	v_mul_f32_e32 v68, v3, v68
	v_lshlrev_b32_e32 v76, 16, v136
	v_and_b32_e32 v72, 0xffff0000, v136
	v_mul_f32_e32 v64, v64, v76
	v_mul_f32_e32 v68, v68, v72
	v_cvt_pk_bf16_f32 v64, v64, v68
	global_store_dword v[98:99], v64, off
	v_fmamk_f32 v81, v73, 0x3c000000, v14
	v_mul_f32_e32 v77, 0x4b800000, v81
	v_cmp_gt_f32_e32 vcc, s14, v81
	s_nop 1
	v_cndmask_b32_e32 v81, v81, v77, vcc
	v_rsq_f32_e32 v81, v81
	s_nop 0
	v_mul_f32_e32 v77, 0x45800000, v81
	v_cndmask_b32_e32 v81, v81, v77, vcc
	v_mul_f32_e32 v65, v65, v81
	v_mul_f32_e32 v69, v69, v81
	v_mul_f32_e32 v65, v2, v65
	v_mul_f32_e32 v69, v3, v69
	v_lshlrev_b32_e32 v77, 16, v137
	v_and_b32_e32 v73, 0xffff0000, v137
	v_mul_f32_e32 v65, v65, v77
	v_mul_f32_e32 v69, v69, v73
	v_cvt_pk_bf16_f32 v65, v65, v69
	global_store_dword v[98:99], v65, off offset:256
	v_fmamk_f32 v82, v74, 0x3c000000, v14
	v_mul_f32_e32 v78, 0x4b800000, v82
	v_cmp_gt_f32_e32 vcc, s14, v82
	s_nop 1
	v_cndmask_b32_e32 v82, v82, v78, vcc
	v_rsq_f32_e32 v82, v82
	s_nop 0
	v_mul_f32_e32 v78, 0x45800000, v82
	v_cndmask_b32_e32 v82, v82, v78, vcc
	v_mul_f32_e32 v66, v66, v82
	v_mul_f32_e32 v70, v70, v82
	v_mul_f32_e32 v66, v2, v66
	v_mul_f32_e32 v70, v3, v70
	v_lshlrev_b32_e32 v78, 16, v138
	v_and_b32_e32 v74, 0xffff0000, v138
	v_mul_f32_e32 v66, v66, v78
	v_mul_f32_e32 v70, v70, v74
	v_cvt_pk_bf16_f32 v66, v66, v70
	global_store_dword v[98:99], v66, off offset:512
	v_fmamk_f32 v83, v75, 0x3c000000, v14
	v_mul_f32_e32 v79, 0x4b800000, v83
	v_cmp_gt_f32_e32 vcc, s14, v83
	s_nop 1
	v_cndmask_b32_e32 v83, v83, v79, vcc
	v_rsq_f32_e32 v83, v83
	s_nop 0
	v_mul_f32_e32 v79, 0x45800000, v83
	v_cndmask_b32_e32 v83, v83, v79, vcc
	v_mul_f32_e32 v67, v67, v83
	v_mul_f32_e32 v71, v71, v83
	v_mul_f32_e32 v67, v2, v67
	v_mul_f32_e32 v71, v3, v71
	v_lshlrev_b32_e32 v79, 16, v139
	v_and_b32_e32 v75, 0xffff0000, v139
	v_mul_f32_e32 v67, v67, v79
	v_mul_f32_e32 v71, v71, v75
	v_cvt_pk_bf16_f32 v67, v67, v71
	global_store_dword v[98:99], v67, off offset:768
	v_lshl_add_u64 v[98:99], v[98:99], 0, s[16:17]
	s_waitcnt vmcnt(12)
; DI unsigned cvt_pk_bf16(float lo, float hi) { unsigned r; asm("v_cvt_pk_bf16_f32 %0, %1, %2" : "=v"(r) : "v"(lo), "v"(hi)); return r; }
; DI void phase_combine(const Params& p) {
;     ...
; #pragma unroll
;     for (int hh = 0; hh < 4; ++hh) {
;       const float o0 = __uint_as_float(a[hh] << 16) + __uint_as_float(b[hh] << 16), o1 = __uint_as_float(a[hh] & 0xffff0000u) + __uint_as_float(b[hh] & 0xffff0000u);
;       const float ss = wave_sum(o0 * o0 + o1 * o1);
;       const float rstd = rsqrtf(ss * (1.f / 128.f) + EPSN);
;       const float g0 = __uint_as_float(g[hh] << 16), g1 = __uint_as_float(g[hh] & 0xffff0000u);
;       *(unsigned*)(OC + (size_t)tok * 1024 + 512 + hh * 128 + lane * 2) = cvt_pk_bf16(o0 * rstd * w0 * g0, o1 * rstd * w1 * g1);
;     }
	v_lshlrev_b32_e32 v64, 16, v140
	v_lshlrev_b32_e32 v76, 16, v144
	v_and_b32_e32 v68, 0xffff0000, v140
	v_and_b32_e32 v80, 0xffff0000, v144
	v_add_f32_e32 v64, v64, v76
	v_add_f32_e32 v68, v68, v80
	v_mul_f32_e32 v72, v64, v64
	v_mul_f32_e32 v76, v68, v68
	v_add_f32_e32 v72, v72, v76
	v_lshlrev_b32_e32 v65, 16, v141
	v_lshlrev_b32_e32 v77, 16, v145
	v_and_b32_e32 v69, 0xffff0000, v141
	v_and_b32_e32 v81, 0xffff0000, v145
	v_add_f32_e32 v65, v65, v77
	v_add_f32_e32 v69, v69, v81
	v_mul_f32_e32 v73, v65, v65
	v_mul_f32_e32 v77, v69, v69
	v_add_f32_e32 v73, v73, v77
	v_lshlrev_b32_e32 v66, 16, v142
	v_lshlrev_b32_e32 v78, 16, v146
	v_and_b32_e32 v70, 0xffff0000, v142
	v_and_b32_e32 v82, 0xffff0000, v146
	v_add_f32_e32 v66, v66, v78
	v_add_f32_e32 v70, v70, v82
	v_mul_f32_e32 v74, v66, v66
	v_mul_f32_e32 v78, v70, v70
	v_add_f32_e32 v74, v74, v78
	v_lshlrev_b32_e32 v67, 16, v143
	v_lshlrev_b32_e32 v79, 16, v147
	v_and_b32_e32 v71, 0xffff0000, v143
	v_and_b32_e32 v83, 0xffff0000, v147
	v_add_f32_e32 v67, v67, v79
	v_add_f32_e32 v71, v71, v83
	v_mul_f32_e32 v75, v67, v67
	v_mul_f32_e32 v79, v71, v71
	v_add_f32_e32 v75, v75, v79
	ds_bpermute_b32 v76, v8, v72
	ds_bpermute_b32 v77, v8, v73
	ds_bpermute_b32 v78, v8, v74
	ds_bpermute_b32 v79, v8, v75
	s_waitcnt lgkmcnt(3)
	v_add_f32_e32 v72, v72, v76
	s_waitcnt lgkmcnt(2)
	v_add_f32_e32 v73, v73, v77
	s_waitcnt lgkmcnt(1)
	v_add_f32_e32 v74, v74, v78
	s_waitcnt lgkmcnt(0)
	v_add_f32_e32 v75, v75, v79
	ds_bpermute_b32 v76, v9, v72
	ds_bpermute_b32 v77, v9, v73
	ds_bpermute_b32 v78, v9, v74
	ds_bpermute_b32 v79, v9, v75
	s_waitcnt lgkmcnt(3)
	v_add_f32_e32 v72, v72, v76
	s_waitcnt lgkmcnt(2)
	v_add_f32_e32 v73, v73, v77
	s_waitcnt lgkmcnt(1)
	v_add_f32_e32 v74, v74, v78
	s_waitcnt lgkmcnt(0)
	v_add_f32_e32 v75, v75, v79
	ds_bpermute_b32 v76, v10, v72
	ds_bpermute_b32 v77, v10, v73
	ds_bpermute_b32 v78, v10, v74
	ds_bpermute_b32 v79, v10, v75
	s_waitcnt lgkmcnt(3)
	v_add_f32_e32 v72, v72, v76
	s_waitcnt lgkmcnt(2)
	v_add_f32_e32 v73, v73, v77
	s_waitcnt lgkmcnt(1)
	v_add_f32_e32 v74, v74, v78
	s_waitcnt lgkmcnt(0)
	v_add_f32_e32 v75, v75, v79
	ds_bpermute_b32 v76, v11, v72
	ds_bpermute_b32 v77, v11, v73
	ds_bpermute_b32 v78, v11, v74
	ds_bpermute_b32 v79, v11, v75
	s_waitcnt lgkmcnt(3)
	v_add_f32_e32 v72, v72, v76
	s_waitcnt lgkmcnt(2)
	v_add_f32_e32 v73, v73, v77
	s_waitcnt lgkmcnt(1)
	v_add_f32_e32 v74, v74, v78
	s_waitcnt lgkmcnt(0)
	v_add_f32_e32 v75, v75, v79
	ds_bpermute_b32 v76, v12, v72
	ds_bpermute_b32 v77, v12, v73
	ds_bpermute_b32 v78, v12, v74
	ds_bpermute_b32 v79, v12, v75
	s_waitcnt lgkmcnt(3)
	v_add_f32_e32 v72, v72, v76
	s_waitcnt lgkmcnt(2)
	v_add_f32_e32 v73, v73, v77
	s_waitcnt lgkmcnt(1)
	v_add_f32_e32 v74, v74, v78
	s_waitcnt lgkmcnt(0)
	v_add_f32_e32 v75, v75, v79
	ds_bpermute_b32 v76, v13, v72
	ds_bpermute_b32 v77, v13, v73
	ds_bpermute_b32 v78, v13, v74
	ds_bpermute_b32 v79, v13, v75
	s_waitcnt lgkmcnt(3)
	v_add_f32_e32 v72, v72, v76
	s_waitcnt lgkmcnt(2)
	v_add_f32_e32 v73, v73, v77
	s_waitcnt lgkmcnt(1)
	v_add_f32_e32 v74, v74, v78
	s_waitcnt lgkmcnt(0)
	v_add_f32_e32 v75, v75, v79
	v_fmamk_f32 v80, v72, 0x3c000000, v14
	v_mul_f32_e32 v76, 0x4b800000, v80
	v_cmp_gt_f32_e32 vcc, s14, v80
	s_nop 1
	v_cndmask_b32_e32 v80, v80, v76, vcc
	v_rsq_f32_e32 v80, v80
	s_nop 0
	v_mul_f32_e32 v76, 0x45800000, v80
	v_cndmask_b32_e32 v80, v80, v76, vcc
	v_mul_f32_e32 v64, v64, v80
	v_mul_f32_e32 v68, v68, v80
	v_mul_f32_e32 v64, v2, v64
	v_mul_f32_e32 v68, v3, v68
	v_lshlrev_b32_e32 v76, 16, v148
	v_and_b32_e32 v72, 0xffff0000, v148
	v_mul_f32_e32 v64, v64, v76
	v_mul_f32_e32 v68, v68, v72
	v_cvt_pk_bf16_f32 v64, v64, v68
	global_store_dword v[98:99], v64, off
	v_fmamk_f32 v81, v73, 0x3c000000, v14
	v_mul_f32_e32 v77, 0x4b800000, v81
	v_cmp_gt_f32_e32 vcc, s14, v81
	s_nop 1
	v_cndmask_b32_e32 v81, v81, v77, vcc
	v_rsq_f32_e32 v81, v81
	s_nop 0
	v_mul_f32_e32 v77, 0x45800000, v81
	v_cndmask_b32_e32 v81, v81, v77, vcc
	v_mul_f32_e32 v65, v65, v81
	v_mul_f32_e32 v69, v69, v81
	v_mul_f32_e32 v65, v2, v65
	v_mul_f32_e32 v69, v3, v69
	v_lshlrev_b32_e32 v77, 16, v149
	v_and_b32_e32 v73, 0xffff0000, v149
	v_mul_f32_e32 v65, v65, v77
	v_mul_f32_e32 v69, v69, v73
	v_cvt_pk_bf16_f32 v65, v65, v69
	global_store_dword v[98:99], v65, off offset:256
	v_fmamk_f32 v82, v74, 0x3c000000, v14
	v_mul_f32_e32 v78, 0x4b800000, v82
	v_cmp_gt_f32_e32 vcc, s14, v82
	s_nop 1
	v_cndmask_b32_e32 v82, v82, v78, vcc
	v_rsq_f32_e32 v82, v82
	s_nop 0
	v_mul_f32_e32 v78, 0x45800000, v82
	v_cndmask_b32_e32 v82, v82, v78, vcc
	v_mul_f32_e32 v66, v66, v82
	v_mul_f32_e32 v70, v70, v82
	v_mul_f32_e32 v66, v2, v66
	v_mul_f32_e32 v70, v3, v70
	v_lshlrev_b32_e32 v78, 16, v150
	v_and_b32_e32 v74, 0xffff0000, v150
	v_mul_f32_e32 v66, v66, v78
	v_mul_f32_e32 v70, v70, v74
	v_cvt_pk_bf16_f32 v66, v66, v70
	global_store_dword v[98:99], v66, off offset:512
	v_fmamk_f32 v83, v75, 0x3c000000, v14
	v_mul_f32_e32 v79, 0x4b800000, v83
	v_cmp_gt_f32_e32 vcc, s14, v83
	s_nop 1
	v_cndmask_b32_e32 v83, v83, v79, vcc
	v_rsq_f32_e32 v83, v83
	s_nop 0
	v_mul_f32_e32 v79, 0x45800000, v83
	v_cndmask_b32_e32 v83, v83, v79, vcc
	v_mul_f32_e32 v67, v67, v83
	v_mul_f32_e32 v71, v71, v83
	v_mul_f32_e32 v67, v2, v67
	v_mul_f32_e32 v71, v3, v71
	v_lshlrev_b32_e32 v79, 16, v151
	v_and_b32_e32 v75, 0xffff0000, v151
	v_mul_f32_e32 v67, v67, v79
	v_mul_f32_e32 v71, v71, v75
	v_cvt_pk_bf16_f32 v67, v67, v71
	global_store_dword v[98:99], v67, off offset:768
	v_lshl_add_u64 v[98:99], v[98:99], 0, s[16:17]
	s_branch .LBB0_952
